# split v_pk_add_f32 into scalar v_add_f32 in attention loops
# speedup vs baseline: 1.0122x; 1.0122x over previous
; DI void softmax_tile(f32x16 (&S)[2], float& lsum) {
;     f2_t ps = {0.f, 0.f};
; #pragma unroll
;     for (int t = 0; t < 2; ++t)
; #pragma unroll
;         for (int e = 0; e < 16; e += 2) {
;             f2_t pv; pv.x = __builtin_amdgcn_exp2f(S[t][e]); pv.y = __builtin_amdgcn_exp2f(S[t][e + 1]);
;             S[t][e] = pv.x; S[t][e + 1] = pv.y;
;             ps += pv;
;         }
;     lsum += ps.x + ps.y;
; }
; DI void pv_tile(const f32x16 (&S)[2], f32x16 (&O)[2], const bf16x8 (&vf)[8]) {
; #pragma unroll
;     for (int s = 0; s < 4; ++s) {
;         const bf16x8 pf = pack8(S[s >> 1], s & 1);
; #pragma unroll
; template <int KIND>
; DI void attn_unit(const Params& p, int l, int b, int head, int qt, int qcol, int kcol, int vfeat, int gcol, int mixcol,
;                   int t1, int n1, int t2, int n2, char* smem) {
;     ...
;         const int tile = (it < n1) ? t1 + it : t2 + (it - n1);
;         if (it + 1 < nt) asm volatile("s_waitcnt vmcnt(4)" ::: "memory"); else asm volatile("s_waitcnt vmcnt(0)" ::: "memory");
;         __builtin_amdgcn_s_barrier();
;         const char* sk = smem + sc * ATT_SLOT;
;         const char* sv = sk + ATT_V;
;         bool active = true;
;         if (KIND == 2 && tile < 32) active = (tile >= r0w) && (tile < r0w + 8);
;         bf16x8 kf[8], vf[8];
;         if (active) {
; #pragma unroll
;             for (int s = 0; s < 4; ++s)
; #pragma unroll
;                 for (int t = 0; t < 2; ++t) kf[2 * s + t] = *(const bf16x8*)(sk + (32 * t + r) * 128 + (((2 * s + h) ^ xr) << 4));
;         }
;         __builtin_amdgcn_sched_barrier(0);
;         if (it + 2 < nt) { const int nx = (it + 2 < n1) ? t1 + it + 2 : t2 + (it + 2 - n1); KV_ISSUE(nx, sn); }
;         sc = (sc == 2) ? 0 : sc + 1; sn = (sn == 2) ? 0 : sn + 1;
;         __builtin_amdgcn_sched_barrier(0);
;         if (active) {
;     ...
;             if (KIND == 0) {
;                 f32x16 S0[2], S1[2];
; #pragma unroll
;                 for (int t = 0; t < 2; ++t) { S0[t] = MFMA(kf[t], qf[0], cz); S1[t] = MFMA(kf[4 + t], qf[2], cz); }
; #pragma unroll
;                 for (int t = 0; t < 2; ++t) { S0[t] = MFMA(kf[2 + t], qf[1], S0[t]); S1[t] = MFMA(kf[6 + t], qf[3], S1[t]); }
;                 LOAD_VF();
;                 softmax_tile(S0, l0);
;                 pv_tile(S0, O0, vf);
;                 softmax_tile(S1, l1);
;                 pv_tile(S1, O1, vf);
.LBB0_82:
	v_lshl_add_u32 v92, s35, 14, v221
	v_add_u32_e32 v180, v92, v219
	v_add_u32_e32 v222, v92, v218
	v_add_u32_e32 v223, v92, v216
	v_add_u32_e32 v224, v92, v215
	s_waitcnt vmcnt(4)
	s_barrier
	ds_read_b128 v[80:83], v180
	ds_read_b128 v[84:87], v180 offset:4096
	ds_read_b128 v[160:163], v222
	ds_read_b128 v[164:167], v222 offset:4096
	ds_read_b128 v[88:91], v223
	ds_read_b128 v[168:171], v223 offset:4096
	ds_read_b128 v[172:175], v224
	ds_read_b128 v[176:179], v224 offset:4096
	v_lshl_add_u64 v[96:97], v[198:199], 0, s[4:5]
	s_mov_b64 s[42:43], 0x904000
	v_lshl_add_u32 v100, s34, 14, v220
	v_lshl_add_u64 v[98:99], v[96:97], 0, s[42:43]
	s_mov_b64 s[42:43], 0x905000
	v_lshl_add_u64 v[96:97], v[96:97], 0, s[42:43]
	v_add_u32_e32 v103, 0x1000, v100
	v_readfirstlane_b32 s42, v100
	v_add_u32_e32 v102, 0x2000, v100
	s_mov_b32 m0, s42
	v_readfirstlane_b32 s42, v103
	v_lshl_add_u64 v[92:93], v[196:197], 0, s[4:5]
	v_add_u32_e32 v101, 0x3000, v100
	global_load_lds_dwordx4 v[98:99], off
	s_mov_b32 m0, s42
	v_readfirstlane_b32 s42, v102
	v_lshl_add_u64 v[94:95], v[92:93], 0, s[92:93]
	global_load_lds_dwordx4 v[96:97], off
	s_mov_b32 m0, s42
	v_readfirstlane_b32 s42, v101
	v_lshl_add_u64 v[92:93], v[92:93], 0, s[94:95]
	global_load_lds_dwordx4 v[94:95], off
	s_mov_b32 m0, s42
	s_add_i32 s42, s35, 1
	global_load_lds_dwordx4 v[92:93], off
	s_cmp_lg_u32 s35, 2
	s_cselect_b32 s35, s42, 0
	s_add_i32 s42, s34, 1
	s_waitcnt lgkmcnt(0)
	v_mfma_f32_32x32x16_bf16 v[128:143], v[80:83], v[152:155], v[0:15]
	v_mfma_f32_32x32x16_bf16 v[96:111], v[88:91], v[156:159], v[0:15]
	v_mfma_f32_32x32x16_bf16 v[112:127], v[84:87], v[152:155], v[0:15]
	v_mfma_f32_32x32x16_bf16 v[80:95], v[168:171], v[156:159], v[0:15]
	v_mfma_f32_32x32x16_bf16 v[128:143], v[160:163], v[144:147], v[128:143]
	v_mfma_f32_32x32x16_bf16 v[96:111], v[172:175], v[148:151], v[96:111]
	v_mfma_f32_32x32x16_bf16 v[112:127], v[164:167], v[144:147], v[112:127]
	v_mfma_f32_32x32x16_bf16 v[80:95], v[176:179], v[148:151], v[80:95]
	ds_read_b128 v[188:191], v180 offset:8192
	ds_read_b128 v[184:187], v180 offset:12288
	ds_read_b128 v[180:183], v222 offset:8192
	ds_read_b128 v[176:179], v222 offset:12288
	ds_read_b128 v[172:175], v223 offset:8192
	ds_read_b128 v[168:171], v223 offset:12288
	ds_read_b128 v[164:167], v224 offset:8192
	ds_read_b128 v[160:163], v224 offset:12288
	s_cmp_lg_u32 s34, 2
	s_cselect_b32 s34, s42, 0
	v_exp_f32_e32 v128, v128
	v_exp_f32_e32 v129, v129
	v_exp_f32_e32 v130, v130
	v_exp_f32_e32 v131, v131
	v_exp_f32_e32 v132, v132
	v_exp_f32_e32 v133, v133
	v_exp_f32_e32 v134, v134
	v_exp_f32_e32 v135, v135
	v_add_f32_e64 v222, v128, 0
	v_add_f32_e64 v223, v129, 0
	v_cvt_pk_bf16_f32 v128, v128, v129
	v_add_f32_e64 v222, v130, v222
	v_add_f32_e64 v223, v131, v223
	v_cvt_pk_bf16_f32 v129, v130, v131
	v_cvt_pk_bf16_f32 v130, v132, v133
	v_cvt_pk_bf16_f32 v131, v134, v135
	v_add_f32_e64 v222, v132, v222
	v_add_f32_e64 v223, v133, v223
	v_exp_f32_e32 v136, v136
	s_waitcnt lgkmcnt(0)
	v_mfma_f32_32x32x16_bf16 v[48:63], v[188:191], v[128:131], v[48:63]
	v_exp_f32_e32 v137, v137
	v_exp_f32_e32 v138, v138
	v_exp_f32_e32 v139, v139
	v_exp_f32_e32 v132, v140
	v_exp_f32_e32 v133, v141
	v_exp_f32_e32 v140, v142
	v_exp_f32_e32 v141, v143
	v_mfma_f32_32x32x16_bf16 v[32:47], v[184:187], v[128:131], v[32:47]
	v_add_f32_e64 v134, v134, v222
	v_add_f32_e64 v135, v135, v223
	v_cvt_pk_bf16_f32 v128, v136, v137
	v_cvt_pk_bf16_f32 v129, v138, v139
	v_cvt_pk_bf16_f32 v130, v132, v133
	v_cvt_pk_bf16_f32 v131, v140, v141
	v_add_f32_e64 v134, v136, v134
	v_add_f32_e64 v135, v137, v135
	v_exp_f32_e32 v112, v112
	v_mfma_f32_32x32x16_bf16 v[48:63], v[180:183], v[128:131], v[48:63]
	v_add_f32_e64 v134, v138, v134
	v_add_f32_e64 v135, v139, v135
	v_exp_f32_e32 v113, v113
	v_add_f32_e64 v134, v132, v134
	v_add_f32_e64 v135, v133, v135
	v_exp_f32_e32 v116, v116
	v_add_f32_e64 v132, v140, v134
	v_add_f32_e64 v133, v141, v135
	v_exp_f32_e32 v134, v114
	v_exp_f32_e32 v135, v115
	v_mfma_f32_32x32x16_bf16 v[32:47], v[176:179], v[128:131], v[32:47]
	v_exp_f32_e32 v117, v117
	v_exp_f32_e32 v118, v118
	v_exp_f32_e32 v119, v119
	v_add_f32_e64 v132, v112, v132
	v_add_f32_e64 v133, v113, v133
	v_cvt_pk_bf16_f32 v112, v112, v113
	v_cvt_pk_bf16_f32 v113, v134, v135
	v_cvt_pk_bf16_f32 v114, v116, v117
	v_cvt_pk_bf16_f32 v115, v118, v119
	v_add_f32_e64 v128, v134, v132
	v_add_f32_e64 v129, v135, v133
	v_exp_f32_e32 v120, v120
	v_mfma_f32_32x32x16_bf16 v[48:63], v[172:175], v[112:115], v[48:63]
	v_add_f32_e64 v116, v116, v128
	v_add_f32_e64 v117, v117, v129
	v_exp_f32_e32 v121, v121
	v_add_f32_e64 v116, v118, v116
	v_add_f32_e64 v117, v119, v117
	v_exp_f32_e32 v118, v122
	v_exp_f32_e32 v119, v123
	v_exp_f32_e32 v122, v124
	v_exp_f32_e32 v123, v125
	v_mfma_f32_32x32x16_bf16 v[32:47], v[168:171], v[112:115], v[32:47]
	v_exp_f32_e32 v124, v126
	v_exp_f32_e32 v125, v127
	v_exp_f32_e32 v96, v96
	v_exp_f32_e32 v97, v97
	v_exp_f32_e32 v98, v98
	v_exp_f32_e32 v99, v99
	v_exp_f32_e32 v100, v100
	v_exp_f32_e32 v101, v101
	v_exp_f32_e32 v102, v102
	v_exp_f32_e32 v103, v103
	v_cvt_pk_bf16_f32 v112, v120, v121
	v_cvt_pk_bf16_f32 v113, v118, v119
	v_cvt_pk_bf16_f32 v114, v122, v123
	v_cvt_pk_bf16_f32 v115, v124, v125
	v_exp_f32_e32 v104, v104
	v_exp_f32_e32 v105, v105
	v_mfma_f32_32x32x16_bf16 v[48:63], v[164:167], v[112:115], v[48:63]
	v_exp_f32_e32 v106, v106
	v_exp_f32_e32 v107, v107
	v_exp_f32_e32 v108, v108
	v_exp_f32_e32 v109, v109
	v_exp_f32_e32 v84, v84
	v_exp_f32_e32 v85, v85
	v_exp_f32_e32 v86, v86
	v_mfma_f32_32x32x16_bf16 v[32:47], v[160:163], v[112:115], v[32:47]
	v_add_f32_e64 v112, v96, 0
	v_add_f32_e64 v113, v97, 0
; #define MFMA(a, b, c) __builtin_amdgcn_mfma_f32_32x32x16_bf16((a), (b), (c), 0, 0, 0)
; DI void softmax_tile(f32x16 (&S)[2], float& lsum) {
;     f2_t ps = {0.f, 0.f};
; #pragma unroll
;     for (int t = 0; t < 2; ++t)
; #pragma unroll
;         for (int e = 0; e < 16; e += 2) {
;             f2_t pv; pv.x = __builtin_amdgcn_exp2f(S[t][e]); pv.y = __builtin_amdgcn_exp2f(S[t][e + 1]);
;             S[t][e] = pv.x; S[t][e + 1] = pv.y;
;             ps += pv;
;         }
;     lsum += ps.x + ps.y;
; }
; DI void pv_tile(const f32x16 (&S)[2], f32x16 (&O)[2], const bf16x8 (&vf)[8]) {
; #pragma unroll
;     for (int s = 0; s < 4; ++s) {
;         const bf16x8 pf = pack8(S[s >> 1], s & 1);
; #pragma unroll
;         for (int dt = 0; dt < 2; ++dt) O[dt] = MFMA(vf[2 * s + dt], pf, O[dt]);
;     }
; }
; template <int KIND>
; DI void attn_unit(const Params& p, int l, int b, int head, int qt, int qcol, int kcol, int vfeat, int gcol, int mixcol,
;                   int t1, int n1, int t2, int n2, char* smem) {
;     ...
;                 softmax_tile(S0, l0);
;                 pv_tile(S0, O0, vf);
;                 softmax_tile(S1, l1);
;                 pv_tile(S1, O1, vf);
	v_cvt_pk_bf16_f32 v96, v96, v97
	v_add_f32_e64 v112, v98, v112
	v_add_f32_e64 v113, v99, v113
	v_cvt_pk_bf16_f32 v97, v98, v99
	v_cvt_pk_bf16_f32 v98, v100, v101
	v_cvt_pk_bf16_f32 v99, v102, v103
	v_add_f32_e64 v112, v100, v112
	v_add_f32_e64 v113, v101, v113
	v_exp_f32_e32 v100, v110
	v_mfma_f32_32x32x16_bf16 v[64:79], v[188:191], v[96:99], v[64:79]
	v_add_f32_e64 v112, v102, v112
	v_add_f32_e64 v113, v103, v113
	v_exp_f32_e32 v101, v111
	v_add_f32_e64 v112, v104, v112
	v_add_f32_e64 v113, v105, v113
	v_exp_f32_e32 v102, v80
	v_exp_f32_e32 v103, v81
	v_add_f32_e64 v112, v106, v112
	v_add_f32_e64 v113, v107, v113
	v_exp_f32_e32 v87, v87
	v_mfma_f32_32x32x16_bf16 v[16:31], v[184:187], v[96:99], v[16:31]
	v_add_f32_e64 v80, v108, v112
	v_add_f32_e64 v81, v109, v113
	v_exp_f32_e32 v98, v82
	v_add_f32_e64 v80, v100, v80
	v_add_f32_e64 v81, v101, v81
	v_exp_f32_e32 v99, v83
	v_add_f32_e64 v96, v102, v80
	v_add_f32_e64 v97, v103, v81
	v_cvt_pk_bf16_f32 v80, v104, v105
	v_cvt_pk_bf16_f32 v81, v106, v107
	v_cvt_pk_bf16_f32 v82, v108, v109
	v_cvt_pk_bf16_f32 v83, v100, v101
	v_exp_f32_e32 v88, v88
	v_exp_f32_e32 v89, v89
	v_mfma_f32_32x32x16_bf16 v[64:79], v[180:183], v[80:83], v[64:79]
	v_add_f32_e64 v96, v98, v96
	v_add_f32_e64 v97, v99, v97
	v_add_f32_e64 v116, v120, v116
	v_add_f32_e64 v117, v121, v117
	s_add_u32 s4, s4, 0x2000
	v_add_f32_e64 v116, v118, v116
	v_add_f32_e64 v117, v119, v117
	s_addc_u32 s5, s5, 0
	v_add_f32_e64 v116, v122, v116
	v_add_f32_e64 v117, v123, v117
	s_cmp_eq_u32 s52, s4
	v_mfma_f32_32x32x16_bf16 v[16:31], v[176:179], v[80:83], v[16:31]
	v_add_f32_e64 v80, v84, v96
	v_add_f32_e64 v81, v85, v97
	v_cvt_pk_bf16_f32 v82, v84, v85
	v_add_f32_e64 v80, v86, v80
	v_add_f32_e64 v81, v87, v81
	v_cvt_pk_bf16_f32 v83, v86, v87
	v_add_f32_e64 v96, v88, v80
	v_add_f32_e64 v97, v89, v81
	v_cvt_pk_bf16_f32 v80, v102, v103
	v_cvt_pk_bf16_f32 v81, v98, v99
	v_exp_f32_e32 v84, v90
	v_exp_f32_e32 v85, v91
	v_mfma_f32_32x32x16_bf16 v[64:79], v[172:175], v[80:83], v[64:79]
	v_exp_f32_e32 v86, v92
	v_exp_f32_e32 v87, v93
	v_exp_f32_e32 v90, v94
	v_exp_f32_e32 v91, v95
	v_add_f32_e64 v92, v84, v96
	v_add_f32_e64 v93, v85, v97
	v_add_f32_e64 v116, v124, v116
	v_add_f32_e64 v117, v125, v117
	v_mfma_f32_32x32x16_bf16 v[16:31], v[168:171], v[80:83], v[16:31]
	v_add_f32_e64 v80, v86, v92
	v_add_f32_e64 v81, v87, v93
	v_cvt_pk_bf16_f32 v82, v86, v87
	v_add_f32_e64 v92, v90, v80
	v_add_f32_e64 v93, v91, v81
	v_cvt_pk_bf16_f32 v80, v88, v89
	v_cvt_pk_bf16_f32 v81, v84, v85
	v_cvt_pk_bf16_f32 v83, v90, v91
	v_mov_b32_e32 v94, v92
	v_mov_b32_e32 v95, v116
	v_mfma_f32_32x32x16_bf16 v[64:79], v[164:167], v[80:83], v[64:79]
	v_mov_b32_e32 v116, v93
	v_add_f32_e64 v84, v94, v116
	v_add_f32_e64 v85, v95, v117
	v_add_f32_e64 v194, v194, v84
	v_add_f32_e64 v195, v195, v85
	v_mfma_f32_32x32x16_bf16 v[16:31], v[160:163], v[80:83], v[16:31]
	s_cbranch_scc0 .LBB0_82
	s_lshl_b32 s4, s35, 14
	s_add_i32 s5, s4, 32
	v_add_u32_e32 v92, s5, v217
	v_add_u32_e32 v180, v92, v219
	v_add_u32_e32 v196, v92, v218
	v_add_u32_e32 v197, v92, v216
	v_add_u32_e32 v198, v92, v215
	s_waitcnt vmcnt(4)
	s_barrier
	ds_read_b128 v[80:83], v180
	ds_read_b128 v[84:87], v180 offset:4096
	ds_read_b128 v[160:163], v196
	ds_read_b128 v[164:167], v196 offset:4096
	ds_read_b128 v[88:91], v197
	ds_read_b128 v[168:171], v197 offset:4096
	ds_read_b128 v[172:175], v198
	ds_read_b128 v[176:179], v198 offset:4096
	s_waitcnt lgkmcnt(0)
	v_mfma_f32_32x32x16_bf16 v[128:143], v[80:83], v[152:155], v[0:15]
	v_mfma_f32_32x32x16_bf16 v[96:111], v[88:91], v[156:159], v[0:15]
	v_mfma_f32_32x32x16_bf16 v[112:127], v[84:87], v[152:155], v[0:15]
	v_mfma_f32_32x32x16_bf16 v[80:95], v[168:171], v[156:159], v[0:15]
	v_mfma_f32_32x32x16_bf16 v[128:143], v[160:163], v[144:147], v[128:143]
	v_mfma_f32_32x32x16_bf16 v[96:111], v[172:175], v[148:151], v[96:111]
	v_mfma_f32_32x32x16_bf16 v[112:127], v[164:167], v[144:147], v[112:127]
	v_mfma_f32_32x32x16_bf16 v[80:95], v[176:179], v[148:151], v[80:95]
	ds_read_b128 v[188:191], v180 offset:8192
	ds_read_b128 v[184:187], v180 offset:12288
	ds_read_b128 v[180:183], v196 offset:8192
	ds_read_b128 v[176:179], v196 offset:12288
	ds_read_b128 v[172:175], v197 offset:8192
	ds_read_b128 v[168:171], v197 offset:12288
	ds_read_b128 v[164:167], v198 offset:8192
	ds_read_b128 v[160:163], v198 offset:12288
	s_nop 0
	v_exp_f32_e32 v128, v128
	v_exp_f32_e32 v129, v129
	v_exp_f32_e32 v130, v130
	v_exp_f32_e32 v131, v131
	v_exp_f32_e32 v132, v132
	v_exp_f32_e32 v133, v133
	v_exp_f32_e32 v134, v134
	v_exp_f32_e32 v135, v135
	v_add_f32_e64 v196, v128, 0
	v_add_f32_e64 v197, v129, 0
	v_cvt_pk_bf16_f32 v128, v128, v129
	v_add_f32_e64 v196, v130, v196
	v_add_f32_e64 v197, v131, v197
	v_cvt_pk_bf16_f32 v129, v130, v131
	v_cvt_pk_bf16_f32 v130, v132, v133
	v_cvt_pk_bf16_f32 v131, v134, v135
	v_add_f32_e64 v196, v132, v196
	v_add_f32_e64 v197, v133, v197
	v_exp_f32_e32 v136, v136
	s_waitcnt lgkmcnt(0)
; #define MFMA(a, b, c) __builtin_amdgcn_mfma_f32_32x32x16_bf16((a), (b), (c), 0, 0, 0)
; #define KV_ISSUE(tile_, slot_) do { \
;     const bf16_t* kp_ = kbase + (size_t)(tile_) * 4096 + kvoff; const bf16_t* vp_ = vbase + (size_t)(tile_) * 4096 + kvoff; \
;     char* lp_ = smem + (slot_) * ATT_SLOT + tid * 16; \
;     dma16(kp_, lp_); dma16(kp_ + 2048, lp_ + 4096); dma16(vp_, lp_ + ATT_V); dma16(vp_ + 2048, lp_ + ATT_V + 4096); } while (0)
; template <int KIND>
; DI void attn_unit(const Params& p, int l, int b, int head, int qt, int qcol, int kcol, int vfeat, int gcol, int mixcol,
;                   int t1, int n1, int t2, int n2, char* smem) {
;     ...
;         const int tile = (it < n1) ? t1 + it : t2 + (it - n1);
;         if (it + 1 < nt) asm volatile("s_waitcnt vmcnt(4)" ::: "memory"); else asm volatile("s_waitcnt vmcnt(0)" ::: "memory");
;         __builtin_amdgcn_s_barrier();
;         const char* sk = smem + sc * ATT_SLOT;
;         const char* sv = sk + ATT_V;
;         bool active = true;
;         if (KIND == 2 && tile < 32) active = (tile >= r0w) && (tile < r0w + 8);
;         bf16x8 kf[8], vf[8];
;         if (active) {
; #pragma unroll
;             for (int s = 0; s < 4; ++s)
; #pragma unroll
;                 for (int t = 0; t < 2; ++t) kf[2 * s + t] = *(const bf16x8*)(sk + (32 * t + r) * 128 + (((2 * s + h) ^ xr) << 4));
;         }
;         __builtin_amdgcn_sched_barrier(0);
;         if (it + 2 < nt) { const int nx = (it + 2 < n1) ? t1 + it + 2 : t2 + (it + 2 - n1); KV_ISSUE(nx, sn); }
;         sc = (sc == 2) ? 0 : sc + 1; sn = (sn == 2) ? 0 : sn + 1;
;         __builtin_amdgcn_sched_barrier(0);
;         if (active) {
;     ...
;             if (KIND == 0) {
;                 f32x16 S0[2], S1[2];
; #pragma unroll
;                 for (int t = 0; t < 2; ++t) { S0[t] = MFMA(kf[t], qf[0], cz); S1[t] = MFMA(kf[4 + t], qf[2], cz); }
; #pragma unroll
;                 for (int t = 0; t < 2; ++t) { S0[t] = MFMA(kf[2 + t], qf[1], S0[t]); S1[t] = MFMA(kf[6 + t], qf[3], S1[t]); }
;                 LOAD_VF();
;                 softmax_tile(S0, l0);
;                 pv_tile(S0, O0, vf);
;                 softmax_tile(S1, l1);
;                 pv_tile(S1, O1, vf);
	v_mfma_f32_32x32x16_bf16 v[48:63], v[188:191], v[128:131], v[48:63]
	v_exp_f32_e32 v137, v137
	v_exp_f32_e32 v138, v138
	v_exp_f32_e32 v139, v139
	v_exp_f32_e32 v132, v140
	v_exp_f32_e32 v133, v141
	v_exp_f32_e32 v140, v142
	v_exp_f32_e32 v141, v143
	v_mfma_f32_32x32x16_bf16 v[32:47], v[184:187], v[128:131], v[32:47]
	v_add_f32_e64 v134, v134, v196
	v_add_f32_e64 v135, v135, v197
	v_cvt_pk_bf16_f32 v128, v136, v137
	v_cvt_pk_bf16_f32 v129, v138, v139
	v_cvt_pk_bf16_f32 v130, v132, v133
	v_cvt_pk_bf16_f32 v131, v140, v141
	v_add_f32_e64 v134, v136, v134
	v_add_f32_e64 v135, v137, v135
	v_exp_f32_e32 v112, v112
	v_mfma_f32_32x32x16_bf16 v[48:63], v[180:183], v[128:131], v[48:63]
	v_add_f32_e64 v134, v138, v134
	v_add_f32_e64 v135, v139, v135
	v_exp_f32_e32 v113, v113
	v_add_f32_e64 v134, v132, v134
	v_add_f32_e64 v135, v133, v135
	v_exp_f32_e32 v116, v116
	v_add_f32_e64 v132, v140, v134
	v_add_f32_e64 v133, v141, v135
	v_exp_f32_e32 v134, v114
	v_exp_f32_e32 v135, v115
	v_mfma_f32_32x32x16_bf16 v[32:47], v[176:179], v[128:131], v[32:47]
	v_exp_f32_e32 v117, v117
	v_exp_f32_e32 v118, v118
	v_exp_f32_e32 v119, v119
	v_add_f32_e64 v132, v112, v132
	v_add_f32_e64 v133, v113, v133
	v_cvt_pk_bf16_f32 v112, v112, v113
	v_cvt_pk_bf16_f32 v113, v134, v135
	v_cvt_pk_bf16_f32 v114, v116, v117
	v_cvt_pk_bf16_f32 v115, v118, v119
	v_add_f32_e64 v128, v134, v132
	v_add_f32_e64 v129, v135, v133
	v_exp_f32_e32 v120, v120
	v_mfma_f32_32x32x16_bf16 v[48:63], v[172:175], v[112:115], v[48:63]
	v_add_f32_e64 v116, v116, v128
	v_add_f32_e64 v117, v117, v129
	v_exp_f32_e32 v121, v121
	v_add_f32_e64 v116, v118, v116
	v_add_f32_e64 v117, v119, v117
	v_exp_f32_e32 v118, v122
	v_exp_f32_e32 v119, v123
	v_exp_f32_e32 v122, v124
	v_exp_f32_e32 v123, v125
	v_mfma_f32_32x32x16_bf16 v[32:47], v[168:171], v[112:115], v[32:47]
	v_exp_f32_e32 v124, v126
	v_exp_f32_e32 v125, v127
	v_exp_f32_e32 v96, v96
	v_exp_f32_e32 v97, v97
	v_exp_f32_e32 v98, v98
	v_exp_f32_e32 v99, v99
	v_exp_f32_e32 v100, v100
	v_exp_f32_e32 v101, v101
	v_exp_f32_e32 v102, v102
	v_exp_f32_e32 v103, v103
	v_cvt_pk_bf16_f32 v112, v120, v121
	v_cvt_pk_bf16_f32 v113, v118, v119
	v_cvt_pk_bf16_f32 v114, v122, v123
	v_cvt_pk_bf16_f32 v115, v124, v125
	v_exp_f32_e32 v104, v104
	v_exp_f32_e32 v105, v105
	v_mfma_f32_32x32x16_bf16 v[48:63], v[164:167], v[112:115], v[48:63]
	v_exp_f32_e32 v106, v106
	v_exp_f32_e32 v107, v107
	v_exp_f32_e32 v80, v80
	v_exp_f32_e32 v81, v81
	v_exp_f32_e32 v82, v82
	v_exp_f32_e32 v83, v83
	v_exp_f32_e32 v84, v84
	v_mfma_f32_32x32x16_bf16 v[32:47], v[160:163], v[112:115], v[32:47]
	v_add_f32_e64 v112, v96, 0
	v_add_f32_e64 v113, v97, 0
	v_cvt_pk_bf16_f32 v96, v96, v97
	v_add_f32_e64 v112, v98, v112
	v_add_f32_e64 v113, v99, v113
	v_cvt_pk_bf16_f32 v97, v98, v99
	v_cvt_pk_bf16_f32 v98, v100, v101
	v_cvt_pk_bf16_f32 v99, v102, v103
	v_add_f32_e64 v112, v100, v112
	v_add_f32_e64 v113, v101, v113
	v_exp_f32_e32 v100, v108
	v_mfma_f32_32x32x16_bf16 v[64:79], v[188:191], v[96:99], v[64:79]
	v_exp_f32_e32 v101, v109
	v_add_f32_e64 v112, v102, v112
	v_add_f32_e64 v113, v103, v113
	v_exp_f32_e32 v102, v110
	v_exp_f32_e32 v103, v111
	v_add_f32_e64 v112, v104, v112
	v_add_f32_e64 v113, v105, v113
	v_exp_f32_e32 v85, v85
	v_add_f32_e64 v112, v106, v112
	v_add_f32_e64 v113, v107, v113
	v_mfma_f32_32x32x16_bf16 v[16:31], v[184:187], v[96:99], v[16:31]
	v_add_f32_e64 v108, v100, v112
	v_add_f32_e64 v109, v101, v113
	v_cvt_pk_bf16_f32 v98, v100, v101
	v_add_f32_e64 v96, v102, v108
	v_add_f32_e64 v97, v103, v109
	v_cvt_pk_bf16_f32 v99, v102, v103
	v_add_f32_e64 v108, v80, v96
	v_add_f32_e64 v109, v81, v97
	v_cvt_pk_bf16_f32 v96, v104, v105
	v_cvt_pk_bf16_f32 v97, v106, v107
	v_exp_f32_e32 v86, v86
	v_exp_f32_e32 v87, v87
	v_mfma_f32_32x32x16_bf16 v[64:79], v[180:183], v[96:99], v[64:79]
	v_add_f32_e64 v100, v82, v108
	v_add_f32_e64 v101, v83, v109
	v_exp_f32_e32 v88, v88
	v_add_f32_e64 v100, v84, v100
	v_add_f32_e64 v101, v85, v101
	v_exp_f32_e32 v89, v89
	v_cvt_pk_bf16_f32 v80, v80, v81
	v_cvt_pk_bf16_f32 v81, v82, v83
	v_cvt_pk_bf16_f32 v82, v84, v85
	v_mfma_f32_32x32x16_bf16 v[16:31], v[176:179], v[96:99], v[16:31]
	v_cvt_pk_bf16_f32 v83, v86, v87
	v_add_f32_e64 v96, v86, v100
	v_add_f32_e64 v97, v87, v101
	v_exp_f32_e32 v86, v90
	v_exp_f32_e32 v87, v91
	v_exp_f32_e32 v90, v92
	v_exp_f32_e32 v91, v93
	v_exp_f32_e32 v92, v94
	v_mfma_f32_32x32x16_bf16 v[64:79], v[172:175], v[80:83], v[64:79]
	v_exp_f32_e32 v93, v95
	s_addk_i32 s4, 0x4000
	v_add_f32_e64 v84, v88, v96
	v_add_f32_e64 v85, v89, v97
	s_cmp_lg_u32 s35, 2
	s_cselect_b32 s4, s4, 0
	s_add_i32 s4, s4, 32
	s_waitcnt vmcnt(0)
	v_mfma_f32_32x32x16_bf16 v[16:31], v[168:171], v[80:83], v[16:31]
	v_add_f32_e64 v80, v86, v84
	v_add_f32_e64 v81, v87, v85
	v_cvt_pk_bf16_f32 v82, v90, v91
	v_add_f32_e64 v80, v90, v80
	v_add_f32_e64 v81, v91, v81
	v_cvt_pk_bf16_f32 v83, v92, v93
	v_add_f32_e64 v168, v92, v80
	v_add_f32_e64 v169, v93, v81
	v_cvt_pk_bf16_f32 v80, v88, v89
	v_add_u32_e32 v88, s4, v217
	v_cvt_pk_bf16_f32 v81, v86, v87
	v_add_u32_e32 v174, v88, v219
	v_add_u32_e32 v175, v88, v218
	v_add_u32_e32 v176, v88, v216
	v_add_u32_e32 v177, v88, v215
	v_mfma_f32_32x32x16_bf16 v[64:79], v[164:167], v[80:83], v[64:79]
	s_barrier
; #define MFMA(a, b, c) __builtin_amdgcn_mfma_f32_32x32x16_bf16((a), (b), (c), 0, 0, 0)
; DI int otid() { int t = threadIdx.x; asm volatile("" : "+v"(t)); return t; }
; DI float xsum32(float x) { const unsigned u = __float_as_uint(x); const auto r2 = __builtin_amdgcn_permlane32_swap(u, u, false, false); return __uint_as_float(r2[0]) + __uint_as_float(r2[1]); }
; #define LOAD_VF() do { \
;             __builtin_amdgcn_sched_barrier(0); \
;             _Pragma("unroll") for (int s = 0; s < 4; ++s) \
;                 _Pragma("unroll") for (int dt = 0; dt < 2; ++dt) vf[2 * s + dt] = ldv_frag(sv, 32 * dt + r, 2 * s + h, xr); \
;             __builtin_amdgcn_sched_barrier(0); } while (0)
; template <int KIND>
; DI void attn_unit(const Params& p, int l, int b, int head, int qt, int qcol, int kcol, int vfeat, int gcol, int mixcol,
;                   int t1, int n1, int t2, int n2, char* smem) {
;     ...
;             if (KIND == 0) {
;                 f32x16 S0[2], S1[2];
; #pragma unroll
;                 for (int t = 0; t < 2; ++t) { S0[t] = MFMA(kf[t], qf[0], cz); S1[t] = MFMA(kf[4 + t], qf[2], cz); }
; #pragma unroll
;                 for (int t = 0; t < 2; ++t) { S0[t] = MFMA(kf[2 + t], qf[1], S0[t]); S1[t] = MFMA(kf[6 + t], qf[3], S1[t]); }
;                 LOAD_VF();
;                 softmax_tile(S0, l0);
;                 pv_tile(S0, O0, vf);
;                 softmax_tile(S1, l1);
;                 pv_tile(S1, O1, vf);
;     ...
;     l0 = xsum32(l0);
;     const float inv0 = 1.f / l0;
;     const int tid_e = otid();
;     const size_t qrow_e = (size_t)b * TPB + qt * 128 + 32 * (tid_e >> 6) + (tid_e & 31);
;     bf16_t* orow = p.hmix + ((size_t)(mixcol >> 5) * NTOK + qrow_e) * 32;
;     const bf16_t* grow = p.qkv + ((size_t)(gcol >> 6) * NTOK + qrow_e) * 64;
;     if (KIND == 0) {
;         l1 = xsum32(l1);
;         const float lam = p.lam[l];
;         const float inv1 = lam / l1;
;         float ss = 0.f;
	ds_read_b128 v[84:87], v174
	ds_read_b128 v[128:131], v174 offset:4096
	ds_read_b128 v[132:135], v175
	ds_read_b128 v[136:139], v175 offset:4096
	ds_read_b128 v[96:99], v176
	ds_read_b128 v[140:143], v176 offset:4096
	ds_read_b128 v[164:167], v177
	ds_read_b128 v[170:173], v177 offset:4096
	v_add_f32_e64 v116, v120, v116
	v_add_f32_e64 v117, v121, v117
	s_nop 0
	v_add_f32_e64 v116, v118, v116
	v_add_f32_e64 v117, v119, v117
	v_mfma_f32_32x32x16_bf16 v[16:31], v[160:163], v[80:83], v[16:31]
	v_add_f32_e64 v116, v122, v116
	v_add_f32_e64 v117, v123, v117
	v_add_f32_e64 v196, v124, v116
	v_add_f32_e64 v197, v125, v117
	s_waitcnt lgkmcnt(0)
	v_mfma_f32_32x32x16_bf16 v[112:127], v[84:87], v[152:155], v[0:15]
	v_mfma_f32_32x32x16_bf16 v[80:95], v[96:99], v[156:159], v[0:15]
	v_mfma_f32_32x32x16_bf16 v[96:111], v[128:131], v[152:155], v[0:15]
	v_mfma_f32_32x32x16_bf16 v[0:15], v[140:143], v[156:159], v[0:15]
	v_mfma_f32_32x32x16_bf16 v[112:127], v[132:135], v[144:147], v[112:127]
	v_mfma_f32_32x32x16_bf16 v[80:95], v[164:167], v[148:151], v[80:95]
	v_mfma_f32_32x32x16_bf16 v[96:111], v[136:139], v[144:147], v[96:111]
	v_mfma_f32_32x32x16_bf16 v[0:15], v[170:173], v[148:151], v[0:15]
	ds_read_b128 v[156:159], v174 offset:8192
	ds_read_b128 v[152:155], v174 offset:12288
	ds_read_b128 v[148:151], v175 offset:8192
	ds_read_b128 v[144:147], v175 offset:12288
	ds_read_b128 v[140:143], v176 offset:8192
	ds_read_b128 v[136:139], v176 offset:12288
	ds_read_b128 v[132:135], v177 offset:8192
	ds_read_b128 v[128:131], v177 offset:12288
	s_nop 0
	v_exp_f32_e32 v112, v112
	v_exp_f32_e32 v113, v113
	v_exp_f32_e32 v114, v114
	v_exp_f32_e32 v115, v115
	v_exp_f32_e32 v116, v116
	v_exp_f32_e32 v117, v117
	v_exp_f32_e32 v118, v118
	v_exp_f32_e32 v119, v119
	v_add_f32_e64 v160, v112, 0
	v_add_f32_e64 v161, v113, 0
	v_cvt_pk_bf16_f32 v112, v112, v113
	v_add_f32_e64 v160, v114, v160
	v_add_f32_e64 v161, v115, v161
	v_cvt_pk_bf16_f32 v113, v114, v115
	v_cvt_pk_bf16_f32 v114, v116, v117
	v_cvt_pk_bf16_f32 v115, v118, v119
	v_exp_f32_e32 v120, v120
	v_exp_f32_e32 v121, v121
	s_waitcnt lgkmcnt(0)
	v_mfma_f32_32x32x16_bf16 v[48:63], v[156:159], v[112:115], v[48:63]
	v_exp_f32_e32 v122, v122
	v_exp_f32_e32 v123, v123
	v_exp_f32_e32 v124, v124
	v_exp_f32_e32 v125, v125
	v_exp_f32_e32 v126, v126
	v_exp_f32_e32 v127, v127
	v_add_f32_e64 v160, v116, v160
	v_add_f32_e64 v161, v117, v161
	v_mfma_f32_32x32x16_bf16 v[32:47], v[152:155], v[112:115], v[32:47]
	v_add_f32_e64 v160, v118, v160
	v_add_f32_e64 v161, v119, v161
	v_exp_f32_e32 v118, v96
	v_add_f32_e64 v160, v120, v160
	v_add_f32_e64 v161, v121, v161
	v_exp_f32_e32 v119, v97
	v_add_f32_e64 v116, v122, v160
	v_add_f32_e64 v117, v123, v161
	v_exp_f32_e32 v160, v98
	v_exp_f32_e32 v161, v99
	v_cvt_pk_bf16_f32 v96, v120, v121
	v_cvt_pk_bf16_f32 v97, v122, v123
	v_cvt_pk_bf16_f32 v98, v124, v125
	v_cvt_pk_bf16_f32 v99, v126, v127
	v_add_f32_e64 v116, v124, v116
	v_add_f32_e64 v117, v125, v117
	v_exp_f32_e32 v100, v100
	v_mfma_f32_32x32x16_bf16 v[48:63], v[148:151], v[96:99], v[48:63]
	v_exp_f32_e32 v101, v101
	v_add_f32_e64 v116, v126, v116
	v_add_f32_e64 v117, v127, v117
	v_exp_f32_e32 v102, v102
	v_exp_f32_e32 v103, v103
	v_add_f32_e64 v112, v118, v116
	v_add_f32_e64 v113, v119, v117
	v_exp_f32_e32 v104, v104
	v_exp_f32_e32 v105, v105
	v_mfma_f32_32x32x16_bf16 v[32:47], v[144:147], v[96:99], v[32:47]
	v_add_f32_e64 v112, v160, v112
	v_add_f32_e64 v113, v161, v113
	v_exp_f32_e32 v106, v106
	v_exp_f32_e32 v107, v107
	v_add_f32_e64 v112, v100, v112
	v_add_f32_e64 v113, v101, v113
	v_exp_f32_e32 v108, v108
	v_add_f32_e64 v112, v102, v112
	v_add_f32_e64 v113, v103, v113
	v_cvt_pk_bf16_f32 v96, v118, v119
	v_cvt_pk_bf16_f32 v97, v160, v161
	v_cvt_pk_bf16_f32 v98, v100, v101
	v_cvt_pk_bf16_f32 v99, v102, v103
	v_exp_f32_e32 v109, v109
	v_exp_f32_e32 v100, v110
	v_mfma_f32_32x32x16_bf16 v[48:63], v[140:143], v[96:99], v[48:63]
	v_exp_f32_e32 v101, v111
	v_add_f32_e64 v102, v104, v112
	v_add_f32_e64 v103, v105, v113
	v_exp_f32_e32 v84, v84
	v_add_f32_e64 v102, v106, v102
	v_add_f32_e64 v103, v107, v103
	v_exp_f32_e32 v85, v85
	v_add_f32_e64 v102, v108, v102
	v_add_f32_e64 v103, v109, v103
	v_exp_f32_e32 v86, v86
	v_mfma_f32_32x32x16_bf16 v[32:47], v[136:139], v[96:99], v[32:47]
	v_cvt_pk_bf16_f32 v96, v104, v105
	v_exp_f32_e32 v104, v80
	v_exp_f32_e32 v105, v81
	v_cvt_pk_bf16_f32 v97, v106, v107
	v_exp_f32_e32 v106, v82
	v_exp_f32_e32 v107, v83
	v_exp_f32_e32 v87, v87
	v_add_f32_e64 v102, v100, v102
	v_add_f32_e64 v103, v101, v103
	v_add_f32_e64 v82, v104, 0
	v_add_f32_e64 v83, v105, 0
	v_exp_f32_e32 v88, v88
	v_exp_f32_e32 v89, v89
	v_mov_b32_e32 v110, v196
	v_mov_b32_e32 v111, v102
	v_mov_b32_e32 v102, v197
	v_add_f32_e64 v82, v106, v82
	v_add_f32_e64 v83, v107, v83
	v_exp_f32_e32 v90, v90
	v_exp_f32_e32 v91, v91
	v_cvt_pk_bf16_f32 v99, v100, v101
	v_add_f32_e64 v100, v110, v102
	v_add_f32_e64 v101, v111, v103
	v_add_f32_e64 v82, v84, v82
	v_add_f32_e64 v83, v85, v83
	v_exp_f32_e32 v92, v92
	v_exp_f32_e32 v93, v93
	s_add_u32 s7, s29, s7
	v_pk_add_f32 v[102:103], v[194:195], v[100:101] op_sel:[1,0] op_sel_hi:[0,1]
	v_add_f32_e64 v82, v86, v82
	v_add_f32_e64 v83, v87, v83
	s_addc_u32 s9, s9, 0
	s_add_i32 s8, s8, 0x36000
	s_lshl_b64 s[4:5], s[60:61], 2
	v_cvt_pk_bf16_f32 v98, v108, v109
	v_pk_add_f32 v[80:81], v[102:103], v[100:101] op_sel:[0,1] op_sel_hi:[1,0]
	v_add_f32_e64 v82, v88, v82
	v_add_f32_e64 v83, v89, v83
	s_add_u32 s4, s50, s4
	v_mfma_f32_32x32x16_bf16 v[48:63], v[132:135], v[96:99], v[48:63]
	v_mov_b32_e32 v81, v200
	s_addc_u32 s5, s51, s5
	v_cvt_pk_bf16_f32 v84, v84, v85
	v_cvt_pk_bf16_f32 v85, v86, v87
	v_exp_f32_e32 v94, v94
; DI int otid() { int t = threadIdx.x; asm volatile("" : "+v"(t)); return t; }
; DI float xsum32(float x) { const unsigned u = __float_as_uint(x); const auto r2 = __builtin_amdgcn_permlane32_swap(u, u, false, false); return __uint_as_float(r2[0]) + __uint_as_float(r2[1]); }
; template <int KIND>
; DI void attn_unit(const Params& p, int l, int b, int head, int qt, int qcol, int kcol, int vfeat, int gcol, int mixcol,
;                   int t1, int n1, int t2, int n2, char* smem) {
;     ...
;                 softmax_tile(S0, l0);
;                 pv_tile(S0, O0, vf);
;                 softmax_tile(S1, l1);
;                 pv_tile(S1, O1, vf);
;     ...
;     l0 = xsum32(l0);
;     const float inv0 = 1.f / l0;
;     const int tid_e = otid();
;     const size_t qrow_e = (size_t)b * TPB + qt * 128 + 32 * (tid_e >> 6) + (tid_e & 31);
;     bf16_t* orow = p.hmix + ((size_t)(mixcol >> 5) * NTOK + qrow_e) * 32;
;     const bf16_t* grow = p.qkv + ((size_t)(gcol >> 6) * NTOK + qrow_e) * 64;
;     if (KIND == 0) {
;         l1 = xsum32(l1);
;         const float lam = p.lam[l];
;         const float inv1 = lam / l1;
;         float ss = 0.f;
; #pragma unroll
;         for (int t = 0; t < 2; ++t)
; #pragma unroll
;             for (int e = 0; e < 16; ++e) { const float o = O0[t][e] * inv0 - O1[t][e] * inv1; O0[t][e] = o; ss += o * o; }
;         ss = xsum32(ss);
;         const float rstd = rsqrtf(ss * (1.f / 64.f) + EPS) * p.lam[4 + l];
	v_exp_f32_e32 v95, v95
	v_mfma_f32_32x32x16_bf16 v[32:47], v[128:131], v[96:99], v[32:47]
	v_add_f32_e64 v96, v90, v82
	v_add_f32_e64 v97, v91, v83
	v_exp_f32_e32 v98, v0
	v_exp_f32_e32 v99, v1
	v_add_f32_e64 v0, v92, v96
	v_add_f32_e64 v1, v93, v97
	global_load_dword v96, v193, s[4:5]
	v_cvt_pk_bf16_f32 v82, v104, v105
	v_cvt_pk_bf16_f32 v83, v106, v107
	v_exp_f32_e32 v100, v2
	v_exp_f32_e32 v101, v3
	v_mfma_f32_32x32x16_bf16 v[64:79], v[156:159], v[82:85], v[64:79]
	v_exp_f32_e32 v86, v4
	v_exp_f32_e32 v87, v5
	v_cvt_pk_bf16_f32 v2, v88, v89
	v_cvt_pk_bf16_f32 v3, v90, v91
	v_cvt_pk_bf16_f32 v4, v92, v93
	v_cvt_pk_bf16_f32 v5, v94, v95
	v_add_f32_e64 v0, v94, v0
	v_add_f32_e64 v1, v95, v1
	v_mfma_f32_32x32x16_bf16 v[16:31], v[152:155], v[82:85], v[16:31]
	v_exp_f32_e32 v6, v6
	v_exp_f32_e32 v7, v7
	v_add_f32_e64 v0, v98, v0
	v_add_f32_e64 v1, v99, v1
	v_exp_f32_e32 v8, v8
	v_exp_f32_e32 v9, v9
	v_add_f32_e64 v0, v100, v0
	v_add_f32_e64 v1, v101, v1
	v_exp_f32_e32 v10, v10
	v_mfma_f32_32x32x16_bf16 v[64:79], v[148:151], v[2:5], v[64:79]
	v_exp_f32_e32 v11, v11
	v_add_f32_e64 v82, v86, v0
	v_add_f32_e64 v83, v87, v1
	v_exp_f32_e32 v12, v12
	v_exp_f32_e32 v13, v13
	v_add_f32_e64 v82, v6, v82
	v_add_f32_e64 v83, v7, v83
	v_ashrrev_i32_e32 v0, 1, v81
	v_and_b32_e32 v0, 0xffffffe0, v0
	v_mfma_f32_32x32x16_bf16 v[16:31], v[144:147], v[2:5], v[16:31]
	v_cvt_pk_bf16_f32 v5, v6, v7
	v_exp_f32_e32 v6, v14
	v_exp_f32_e32 v7, v15
	v_add_f32_e64 v14, v8, v82
	v_add_f32_e64 v15, v9, v83
	v_cvt_pk_bf16_f32 v2, v98, v99
	v_add_f32_e64 v14, v10, v14
	v_add_f32_e64 v15, v11, v15
	v_cvt_pk_bf16_f32 v3, v100, v101
	v_cvt_pk_bf16_f32 v4, v86, v87
	v_add_f32_e64 v14, v12, v14
	v_add_f32_e64 v15, v13, v15
	v_ashrrev_i32_e32 v1, 31, v0
	v_mfma_f32_32x32x16_bf16 v[64:79], v[140:143], v[2:5], v[64:79]
	v_add_f32_e64 v14, v6, v14
	v_add_f32_e64 v15, v7, v15
	v_and_or_b32 v84, v81, 31, s7
	v_mov_b32_e32 v85, s9
	v_lshl_add_u64 v[84:85], v[84:85], 0, v[0:1]
	s_mov_b32 s9, s75
	v_lshl_add_u64 v[0:1], v[84:85], 0, s[8:9]
	v_mov_b32_e32 v82, v168
	v_mfma_f32_32x32x16_bf16 v[16:31], v[136:139], v[2:5], v[16:31]
	v_cvt_pk_bf16_f32 v5, v6, v7
	v_mov_b32_e32 v6, v80
	s_nop 1
	v_permlane32_swap_b32_e32 v80, v6
	v_cvt_pk_bf16_f32 v2, v8, v9
	v_add_f32_e32 v8, v80, v6
	v_div_scale_f32 v9, s[8:9], v8, v8, 1.0
	v_cvt_pk_bf16_f32 v3, v10, v11
	v_rcp_f32_e32 v10, v9
	v_cvt_pk_bf16_f32 v4, v12, v13
	v_mov_b32_e32 v83, v14
	v_mov_b32_e32 v14, v169
	v_mfma_f32_32x32x16_bf16 v[64:79], v[132:135], v[2:5], v[64:79]
	v_add_f32_e64 v14, v82, v14
	v_add_f32_e64 v15, v83, v15
	global_load_dword v80, v193, s[4:5] offset:16
	v_add_f32_e64 v6, v194, v14
	v_add_f32_e64 v7, v195, v15
	v_lshlrev_b64 v[0:1], 7, v[0:1]
	v_pk_add_f32 v[6:7], v[6:7], v[14:15] op_sel:[0,1] op_sel_hi:[1,0]
	v_lshl_add_u64 v[0:1], s[40:41], 0, v[0:1]
	v_lshlrev_b32_e32 v88, 3, v214
	v_mfma_f32_32x32x16_bf16 v[16:31], v[128:131], v[2:5], v[16:31]
	v_fma_f32 v2, -v9, v10, 1.0
	v_fmac_f32_e32 v10, v2, v10
	v_div_scale_f32 v2, vcc, 1.0, v8, 1.0
	v_mul_f32_e32 v3, v2, v10
	v_fma_f32 v4, -v9, v3, v2
	v_fmac_f32_e32 v3, v4, v10
	v_fma_f32 v2, -v9, v3, v2
	v_div_fmas_f32 v2, v2, v10, v3
	v_div_fixup_f32 v8, v2, v8, 1.0
	v_mov_b32_e32 v2, v6
	s_nop 1
	v_permlane32_swap_b32_e32 v6, v2
	v_add_f32_e32 v4, v6, v2
	s_waitcnt vmcnt(0)
	v_div_scale_f32 v5, s[4:5], v4, v4, v96
	v_rcp_f32_e32 v6, v5
	v_mov_b32_e32 v89, v193
	v_lshl_add_u64 v[0:1], v[0:1], 0, v[88:89]
	s_mul_i32 s6, s6, 0x9000
	v_fma_f32 v7, -v5, v6, 1.0
	s_mov_b32 s7, s75
	v_fmac_f32_e32 v6, v7, v6
	v_div_scale_f32 v7, vcc, v96, v4, v96
	global_load_dwordx2 v[90:91], v[0:1], off
	v_lshl_add_u64 v[2:3], v[84:85], 0, s[6:7]
	v_mul_f32_e32 v9, v7, v6
	s_load_dwordx2 s[4:5], s[0:1], 0xb8
	s_load_dwordx2 s[6:7], s[0:1], 0x78
	v_fma_f32 v10, -v5, v9, v7
	v_fmac_f32_e32 v9, v10, v6
	v_fma_f32 v5, -v5, v9, v7
	v_lshlrev_b64 v[2:3], 6, v[2:3]
	v_div_fmas_f32 v5, v5, v6, v9
	v_div_fixup_f32 v10, v5, v4, v96
	s_waitcnt lgkmcnt(0)
	v_lshl_add_u64 v[2:3], s[4:5], 0, v[2:3]
	s_add_u32 s4, s6, s46
	s_addc_u32 s5, s7, s47
	v_pk_mul_f32 v[4:5], v[66:67], v[10:11] op_sel_hi:[1,0]
	v_pk_mul_f32 v[16:17], v[16:17], v[10:11] op_sel_hi:[1,0]
	v_pk_fma_f32 v[14:15], v[50:51], v[8:9], v[4:5] op_sel_hi:[1,0,1] neg_lo:[0,0,1] neg_hi:[0,0,1]
	global_load_dwordx4 v[4:7], v192, s[4:5]
	v_pk_mul_f32 v[50:51], v[64:65], v[10:11] op_sel_hi:[1,0]
	v_mul_f32_e32 v64, v15, v15
	v_pk_fma_f32 v[48:49], v[48:49], v[8:9], v[50:51] op_sel_hi:[1,0,1] neg_lo:[0,0,1] neg_hi:[0,0,1]
	v_pk_mul_f32 v[18:19], v[18:19], v[10:11] op_sel_hi:[1,0]
	v_mul_f32_e32 v50, v49, v49
	v_pk_fma_f32 v[50:51], v[48:49], v[48:49], v[50:51] op_sel_hi:[1,1,0]
	v_pk_fma_f32 v[16:17], v[32:33], v[8:9], v[16:17] op_sel_hi:[1,0,1] neg_lo:[0,0,1] neg_hi:[0,0,1]
	v_pk_fma_f32 v[50:51], v[14:15], v[14:15], v[50:51]
	v_pk_fma_f32 v[18:19], v[34:35], v[8:9], v[18:19] op_sel_hi:[1,0,1] neg_lo:[0,0,1] neg_hi:[0,0,1]
	v_pk_add_f32 v[50:51], v[64:65], v[50:51] op_sel_hi:[0,1]
	v_pk_mul_f32 v[64:65], v[70:71], v[10:11] op_sel_hi:[1,0]
	v_mul_f32_e32 v34, v17, v17
	v_pk_fma_f32 v[54:55], v[54:55], v[8:9], v[64:65] op_sel_hi:[1,0,1] neg_lo:[0,0,1] neg_hi:[0,0,1]
	v_pk_mul_f32 v[64:65], v[68:69], v[10:11] op_sel_hi:[1,0]
	v_pk_mul_f32 v[20:21], v[20:21], v[10:11] op_sel_hi:[1,0]
	v_pk_fma_f32 v[52:53], v[52:53], v[8:9], v[64:65] op_sel_hi:[1,0,1] neg_lo:[0,0,1] neg_hi:[0,0,1]
	v_pk_fma_f32 v[20:21], v[36:37], v[8:9], v[20:21] op_sel_hi:[1,0,1] neg_lo:[0,0,1] neg_hi:[0,0,1]
	v_pk_fma_f32 v[50:51], v[52:53], v[52:53], v[50:51]
	v_mul_f32_e32 v64, v53, v53
	v_pk_add_f32 v[50:51], v[64:65], v[50:51] op_sel_hi:[0,1]
	v_pk_fma_f32 v[50:51], v[54:55], v[54:55], v[50:51]
; DI unsigned pk2(float a, float b) { f2_t v = {a, b}; bf2_t r = __builtin_convertvector(v, bf2_t); return __builtin_bit_cast(unsigned, r); }
; DI float bf2f(bf16_t v) { return __uint_as_float(((unsigned)v) << 16); }
; DI float xsum32(float x) { const unsigned u = __float_as_uint(x); const auto r2 = __builtin_amdgcn_permlane32_swap(u, u, false, false); return __uint_as_float(r2[0]) + __uint_as_float(r2[1]); }
; template <int KIND>
; DI void attn_unit(const Params& p, int l, int b, int head, int qt, int qcol, int kcol, int vfeat, int gcol, int mixcol,
;                   int t1, int n1, int t2, int n2, char* smem) {
;     ...
;         float ss = 0.f;
; #pragma unroll
;         for (int t = 0; t < 2; ++t)
; #pragma unroll
;             for (int e = 0; e < 16; ++e) { const float o = O0[t][e] * inv0 - O1[t][e] * inv1; O0[t][e] = o; ss += o * o; }
;         ss = xsum32(ss);
;         const float rstd = rsqrtf(ss * (1.f / 64.f) + EPS) * p.lam[4 + l];
;         const float* sw = p.subln + l * 64;
; #pragma unroll
;         for (int t = 0; t < 2; ++t)
; #pragma unroll
;             for (int q = 0; q < 4; ++q) {
;                 const int f = 32 * t + 8 * q + 4 * h;
;                 const float4 w4 = *(const float4*)(sw + f);
;                 const uint2 gg = *(const uint2*)(grow + f);
;                 const float g0 = bf2f((bf16_t)(gg.x & 0xffff)), g1 = bf2f((bf16_t)(gg.x >> 16)), g2 = bf2f((bf16_t)(gg.y & 0xffff)), g3 = bf2f((bf16_t)(gg.y >> 16));
;                 uint2 o;
;                 o.x = pk2(O0[t][4 * q + 0] * rstd * w4.x * g0, O0[t][4 * q + 1] * rstd * w4.y * g1);
;                 o.y = pk2(O0[t][4 * q + 2] * rstd * w4.z * g2, O0[t][4 * q + 3] * rstd * w4.w * g3);
;                 *(uint2*)(orow + (size_t)t * NTOK * 32 + 8 * q + 4 * h) = o;
;             }
	v_mul_f32_e32 v64, v55, v55
	v_pk_add_f32 v[50:51], v[64:65], v[50:51] op_sel_hi:[0,1]
	v_pk_mul_f32 v[64:65], v[74:75], v[10:11] op_sel_hi:[1,0]
	v_pk_mul_f32 v[22:23], v[22:23], v[10:11] op_sel_hi:[1,0]
	v_pk_fma_f32 v[58:59], v[58:59], v[8:9], v[64:65] op_sel_hi:[1,0,1] neg_lo:[0,0,1] neg_hi:[0,0,1]
	v_pk_mul_f32 v[64:65], v[72:73], v[10:11] op_sel_hi:[1,0]
	v_pk_fma_f32 v[22:23], v[38:39], v[8:9], v[22:23] op_sel_hi:[1,0,1] neg_lo:[0,0,1] neg_hi:[0,0,1]
	v_pk_fma_f32 v[56:57], v[56:57], v[8:9], v[64:65] op_sel_hi:[1,0,1] neg_lo:[0,0,1] neg_hi:[0,0,1]
	v_pk_mul_f32 v[24:25], v[24:25], v[10:11] op_sel_hi:[1,0]
	v_pk_fma_f32 v[50:51], v[56:57], v[56:57], v[50:51]
	v_mul_f32_e32 v64, v57, v57
	v_pk_add_f32 v[50:51], v[64:65], v[50:51] op_sel_hi:[0,1]
	v_pk_fma_f32 v[50:51], v[58:59], v[58:59], v[50:51]
	v_mul_f32_e32 v64, v59, v59
	v_pk_add_f32 v[50:51], v[64:65], v[50:51] op_sel_hi:[0,1]
	v_pk_mul_f32 v[64:65], v[78:79], v[10:11] op_sel_hi:[1,0]
	v_pk_fma_f32 v[24:25], v[40:41], v[8:9], v[24:25] op_sel_hi:[1,0,1] neg_lo:[0,0,1] neg_hi:[0,0,1]
	v_pk_fma_f32 v[62:63], v[62:63], v[8:9], v[64:65] op_sel_hi:[1,0,1] neg_lo:[0,0,1] neg_hi:[0,0,1]
	v_pk_mul_f32 v[64:65], v[76:77], v[10:11] op_sel_hi:[1,0]
	v_pk_mul_f32 v[26:27], v[26:27], v[10:11] op_sel_hi:[1,0]
	v_pk_fma_f32 v[60:61], v[60:61], v[8:9], v[64:65] op_sel_hi:[1,0,1] neg_lo:[0,0,1] neg_hi:[0,0,1]
	v_pk_fma_f32 v[26:27], v[42:43], v[8:9], v[26:27] op_sel_hi:[1,0,1] neg_lo:[0,0,1] neg_hi:[0,0,1]
	v_pk_fma_f32 v[50:51], v[60:61], v[60:61], v[50:51]
	v_mul_f32_e32 v64, v61, v61
	v_pk_add_f32 v[50:51], v[64:65], v[50:51] op_sel_hi:[0,1]
	v_pk_fma_f32 v[50:51], v[62:63], v[62:63], v[50:51]
	v_mul_f32_e32 v64, v63, v63
	v_pk_add_f32 v[50:51], v[64:65], v[50:51] op_sel_hi:[0,1]
	v_pk_fma_f32 v[32:33], v[16:17], v[16:17], v[50:51]
	v_pk_mul_f32 v[30:31], v[30:31], v[10:11] op_sel_hi:[1,0]
	v_pk_add_f32 v[32:33], v[34:35], v[32:33] op_sel_hi:[0,1]
	v_pk_fma_f32 v[32:33], v[18:19], v[18:19], v[32:33]
	v_mul_f32_e32 v34, v19, v19
	v_pk_add_f32 v[32:33], v[34:35], v[32:33] op_sel_hi:[0,1]
	v_pk_fma_f32 v[32:33], v[20:21], v[20:21], v[32:33]
	v_mul_f32_e32 v34, v21, v21
	v_pk_add_f32 v[32:33], v[34:35], v[32:33] op_sel_hi:[0,1]
	v_pk_fma_f32 v[32:33], v[22:23], v[22:23], v[32:33]
	v_mul_f32_e32 v34, v23, v23
	v_pk_add_f32 v[32:33], v[34:35], v[32:33] op_sel_hi:[0,1]
	v_pk_fma_f32 v[32:33], v[24:25], v[24:25], v[32:33]
	v_mul_f32_e32 v34, v25, v25
	v_pk_add_f32 v[32:33], v[34:35], v[32:33] op_sel_hi:[0,1]
	v_pk_fma_f32 v[32:33], v[26:27], v[26:27], v[32:33]
	v_mul_f32_e32 v34, v27, v27
	v_pk_mul_f32 v[10:11], v[28:29], v[10:11] op_sel_hi:[1,0]
	v_pk_add_f32 v[32:33], v[34:35], v[32:33] op_sel_hi:[0,1]
	v_pk_fma_f32 v[30:31], v[46:47], v[8:9], v[30:31] op_sel_hi:[1,0,1] neg_lo:[0,0,1] neg_hi:[0,0,1]
	v_pk_fma_f32 v[8:9], v[44:45], v[8:9], v[10:11] op_sel_hi:[1,0,1] neg_lo:[0,0,1] neg_hi:[0,0,1]
	s_waitcnt vmcnt(1)
	v_lshlrev_b32_e32 v12, 16, v90
	v_pk_fma_f32 v[10:11], v[8:9], v[8:9], v[32:33]
	v_mul_f32_e32 v28, v9, v9
	v_pk_add_f32 v[10:11], v[28:29], v[10:11] op_sel_hi:[0,1]
	v_pk_fma_f32 v[10:11], v[30:31], v[30:31], v[10:11]
	v_mul_f32_e32 v28, v31, v31
	v_pk_add_f32 v[10:11], v[28:29], v[10:11] op_sel_hi:[0,1]
	v_mov_b32_e32 v11, v10
	s_nop 1
	v_permlane32_swap_b32_e32 v10, v11
	v_add_f32_e32 v10, v10, v11
	v_fmamk_f32 v10, v10, 0x3c800000, v201
	v_mul_f32_e32 v11, 0x4b800000, v10
	v_cmp_gt_f32_e32 vcc, s87, v10
	v_and_b32_e32 v13, 0xffff0000, v90
	v_lshl_add_u64 v[2:3], v[2:3], 0, v[88:89]
	v_cndmask_b32_e32 v10, v10, v11, vcc
	v_rsq_f32_e32 v28, v10
	v_lshlrev_b32_e32 v10, 16, v91
	v_and_b32_e32 v11, 0xffff0000, v91
	s_mov_b32 s6, 0x120000
	v_mul_f32_e32 v29, 0x45800000, v28
	v_cndmask_b32_e32 v28, v28, v29, vcc
	v_mul_f32_e32 v28, v80, v28
	v_pk_mul_f32 v[32:33], v[48:49], v[28:29] op_sel_hi:[1,0]
	s_waitcnt vmcnt(0)
	v_pk_mul_f32 v[4:5], v[4:5], v[32:33]
	s_nop 0
	v_pk_mul_f32 v[4:5], v[4:5], v[12:13]
	v_pk_mul_f32 v[12:13], v[14:15], v[28:29] op_sel_hi:[1,0]
	v_cvt_pk_bf16_f32 v4, v4, v5
	v_pk_mul_f32 v[6:7], v[6:7], v[12:13]
	v_pk_mul_f32 v[14:15], v[52:53], v[28:29] op_sel_hi:[1,0]
	v_pk_mul_f32 v[6:7], v[6:7], v[10:11]
	s_nop 0
	v_cvt_pk_bf16_f32 v5, v6, v7
	global_store_dwordx2 v[2:3], v[4:5], off
	global_load_dwordx2 v[10:11], v[0:1], off offset:16
	s_nop 0
	global_load_dwordx4 v[4:7], v192, s[4:5] offset:32
	s_waitcnt vmcnt(1)
	v_lshlrev_b32_e32 v12, 16, v10
	v_and_b32_e32 v13, 0xffff0000, v10
	s_waitcnt vmcnt(0)
; DI unsigned pk2(float a, float b) { f2_t v = {a, b}; bf2_t r = __builtin_convertvector(v, bf2_t); return __builtin_bit_cast(unsigned, r); }
; DI float bf2f(bf16_t v) { return __uint_as_float(((unsigned)v) << 16); }
; template <int KIND>
; DI void attn_unit(const Params& p, int l, int b, int head, int qt, int qcol, int kcol, int vfeat, int gcol, int mixcol,
;                   int t1, int n1, int t2, int n2, char* smem) {
;     ...
;         const float* sw = p.subln + l * 64;
; #pragma unroll
;         for (int t = 0; t < 2; ++t)
; #pragma unroll
;             for (int q = 0; q < 4; ++q) {
;                 const int f = 32 * t + 8 * q + 4 * h;
;                 const float4 w4 = *(const float4*)(sw + f);
;                 const uint2 gg = *(const uint2*)(grow + f);
;                 const float g0 = bf2f((bf16_t)(gg.x & 0xffff)), g1 = bf2f((bf16_t)(gg.x >> 16)), g2 = bf2f((bf16_t)(gg.y & 0xffff)), g3 = bf2f((bf16_t)(gg.y >> 16));
;                 uint2 o;
;                 o.x = pk2(O0[t][4 * q + 0] * rstd * w4.x * g0, O0[t][4 * q + 1] * rstd * w4.y * g1);
;                 o.y = pk2(O0[t][4 * q + 2] * rstd * w4.z * g2, O0[t][4 * q + 3] * rstd * w4.w * g3);
;                 *(uint2*)(orow + (size_t)t * NTOK * 32 + 8 * q + 4 * h) = o;
;             }
	v_pk_mul_f32 v[4:5], v[4:5], v[14:15]
	v_lshlrev_b32_e32 v10, 16, v11
	v_pk_mul_f32 v[4:5], v[4:5], v[12:13]
	v_pk_mul_f32 v[12:13], v[54:55], v[28:29] op_sel_hi:[1,0]
	v_and_b32_e32 v11, 0xffff0000, v11
	v_pk_mul_f32 v[6:7], v[12:13], v[6:7]
	v_cvt_pk_bf16_f32 v4, v4, v5
	v_pk_mul_f32 v[6:7], v[6:7], v[10:11]
	v_pk_mul_f32 v[14:15], v[56:57], v[28:29] op_sel_hi:[1,0]
	v_cvt_pk_bf16_f32 v5, v6, v7
	global_store_dwordx2 v[2:3], v[4:5], off offset:16
	global_load_dwordx2 v[10:11], v[0:1], off offset:32
	s_nop 0
	global_load_dwordx4 v[4:7], v192, s[4:5] offset:64
	s_waitcnt vmcnt(1)
	v_lshlrev_b32_e32 v12, 16, v10
	v_and_b32_e32 v13, 0xffff0000, v10
	s_waitcnt vmcnt(0)
	v_pk_mul_f32 v[4:5], v[14:15], v[4:5]
	v_lshlrev_b32_e32 v10, 16, v11
	v_pk_mul_f32 v[4:5], v[4:5], v[12:13]
	v_pk_mul_f32 v[12:13], v[58:59], v[28:29] op_sel_hi:[1,0]
	v_and_b32_e32 v11, 0xffff0000, v11
	v_pk_mul_f32 v[6:7], v[12:13], v[6:7]
	v_cvt_pk_bf16_f32 v4, v4, v5
	v_pk_mul_f32 v[6:7], v[6:7], v[10:11]
	v_pk_mul_f32 v[12:13], v[60:61], v[28:29] op_sel_hi:[1,0]
	v_cvt_pk_bf16_f32 v5, v6, v7
	global_store_dwordx2 v[2:3], v[4:5], off offset:32
	global_load_dwordx2 v[10:11], v[0:1], off offset:48
	s_nop 0
	global_load_dwordx4 v[4:7], v192, s[4:5] offset:96
	v_pk_mul_f32 v[14:15], v[62:63], v[28:29] op_sel_hi:[1,0]
	s_waitcnt vmcnt(1)
	v_lshlrev_b32_e32 v32, 16, v10
	v_and_b32_e32 v33, 0xffff0000, v10
	v_lshlrev_b32_e32 v10, 16, v11
	v_and_b32_e32 v11, 0xffff0000, v11
	s_waitcnt vmcnt(0)
	v_pk_mul_f32 v[4:5], v[12:13], v[4:5]
	v_pk_mul_f32 v[6:7], v[14:15], v[6:7]
	v_pk_mul_f32 v[4:5], v[4:5], v[32:33]
	v_pk_mul_f32 v[6:7], v[6:7], v[10:11]
	v_cvt_pk_bf16_f32 v4, v4, v5
	v_cvt_pk_bf16_f32 v5, v6, v7
	global_store_dwordx2 v[2:3], v[4:5], off offset:48
	global_load_dwordx2 v[10:11], v[0:1], off offset:64
	s_nop 0
	global_load_dwordx4 v[4:7], v192, s[4:5] offset:128
	v_add_co_u32_e32 v12, vcc, s6, v2
	v_pk_mul_f32 v[14:15], v[18:19], v[28:29] op_sel_hi:[1,0]
	s_nop 0
	v_addc_co_u32_e32 v13, vcc, 0, v3, vcc
	v_pk_mul_f32 v[2:3], v[16:17], v[28:29] op_sel_hi:[1,0]
	s_waitcnt vmcnt(1)
	v_lshlrev_b32_e32 v16, 16, v10
	v_and_b32_e32 v17, 0xffff0000, v10
	v_lshlrev_b32_e32 v10, 16, v11
	v_and_b32_e32 v11, 0xffff0000, v11
	s_waitcnt vmcnt(0)
	v_pk_mul_f32 v[2:3], v[2:3], v[4:5]
	v_pk_mul_f32 v[4:5], v[14:15], v[6:7]
	v_pk_mul_f32 v[2:3], v[2:3], v[16:17]
	v_pk_mul_f32 v[4:5], v[4:5], v[10:11]
	v_cvt_pk_bf16_f32 v2, v2, v3
	v_cvt_pk_bf16_f32 v3, v4, v5
	global_store_dwordx2 v[12:13], v[2:3], off
	global_load_dwordx2 v[6:7], v[0:1], off offset:80
	s_nop 0
	global_load_dwordx4 v[2:5], v192, s[4:5] offset:160
	v_pk_mul_f32 v[10:11], v[20:21], v[28:29] op_sel_hi:[1,0]
	v_pk_mul_f32 v[14:15], v[22:23], v[28:29] op_sel_hi:[1,0]
	s_waitcnt vmcnt(1)
	v_lshlrev_b32_e32 v16, 16, v6
	v_and_b32_e32 v17, 0xffff0000, v6
	v_lshlrev_b32_e32 v6, 16, v7
	v_and_b32_e32 v7, 0xffff0000, v7
	s_waitcnt vmcnt(0)
	v_pk_mul_f32 v[2:3], v[10:11], v[2:3]
	v_pk_mul_f32 v[4:5], v[14:15], v[4:5]
	v_pk_mul_f32 v[2:3], v[2:3], v[16:17]
	v_pk_mul_f32 v[4:5], v[4:5], v[6:7]
	v_cvt_pk_bf16_f32 v2, v2, v3
	v_cvt_pk_bf16_f32 v3, v4, v5
	global_store_dwordx2 v[12:13], v[2:3], off offset:16
	global_load_dwordx2 v[6:7], v[0:1], off offset:96
	s_nop 0
	global_load_dwordx4 v[2:5], v192, s[4:5] offset:192
	v_pk_mul_f32 v[10:11], v[24:25], v[28:29] op_sel_hi:[1,0]
	v_pk_mul_f32 v[14:15], v[26:27], v[28:29] op_sel_hi:[1,0]
	s_waitcnt vmcnt(1)
	v_lshlrev_b32_e32 v16, 16, v6
	v_and_b32_e32 v17, 0xffff0000, v6
	v_lshlrev_b32_e32 v6, 16, v7
	v_and_b32_e32 v7, 0xffff0000, v7
	s_waitcnt vmcnt(0)
	v_pk_mul_f32 v[2:3], v[10:11], v[2:3]
	v_pk_mul_f32 v[4:5], v[14:15], v[4:5]
	v_pk_mul_f32 v[2:3], v[2:3], v[16:17]
	v_pk_mul_f32 v[4:5], v[4:5], v[6:7]
	v_cvt_pk_bf16_f32 v2, v2, v3
	v_cvt_pk_bf16_f32 v3, v4, v5
	global_store_dwordx2 v[12:13], v[2:3], off offset:32
	global_load_dwordx2 v[4:5], v[0:1], off offset:112
	s_nop 0
	global_load_dwordx4 v[0:3], v192, s[4:5] offset:224
	v_pk_mul_f32 v[6:7], v[8:9], v[28:29] op_sel_hi:[1,0]
	v_pk_mul_f32 v[8:9], v[30:31], v[28:29] op_sel_hi:[1,0]
	s_mov_b64 s[4:5], 0
	s_waitcnt vmcnt(1)
	v_lshlrev_b32_e32 v10, 16, v4
	v_and_b32_e32 v11, 0xffff0000, v4
	v_lshlrev_b32_e32 v4, 16, v5
	v_and_b32_e32 v5, 0xffff0000, v5
	s_waitcnt vmcnt(0)
	v_pk_mul_f32 v[0:1], v[6:7], v[0:1]
	v_pk_mul_f32 v[2:3], v[8:9], v[2:3]
	v_pk_mul_f32 v[0:1], v[0:1], v[10:11]
	v_pk_mul_f32 v[2:3], v[2:3], v[4:5]
	v_cvt_pk_bf16_f32 v0, v0, v1
	v_cvt_pk_bf16_f32 v1, v2, v3
	global_store_dwordx2 v[12:13], v[0:1], off offset:48
	s_branch .LBB0_71

; #define MFMA(a, b, c) __builtin_amdgcn_mfma_f32_32x32x16_bf16((a), (b), (c), 0, 0, 0)
; #define LOAD_VF() do { \
;             __builtin_amdgcn_sched_barrier(0); \
;             _Pragma("unroll") for (int s = 0; s < 4; ++s) \
;                 _Pragma("unroll") for (int dt = 0; dt < 2; ++dt) vf[2 * s + dt] = ldv_frag(sv, 32 * dt + r, 2 * s + h, xr); \
;             __builtin_amdgcn_sched_barrier(0); } while (0)
; DI void softmax_tile(f32x16 (&S)[2], float& lsum) {
;     f2_t ps = {0.f, 0.f};
; #pragma unroll
;     for (int t = 0; t < 2; ++t)
; #pragma unroll
;         for (int e = 0; e < 16; e += 2) {
;             f2_t pv; pv.x = __builtin_amdgcn_exp2f(S[t][e]); pv.y = __builtin_amdgcn_exp2f(S[t][e + 1]);
;             S[t][e] = pv.x; S[t][e + 1] = pv.y;
;             ps += pv;
;         }
;     lsum += ps.x + ps.y;
; }
; DI void pv_tile(const f32x16 (&S)[2], f32x16 (&O)[2], const bf16x8 (&vf)[8]) {
; #pragma unroll
;     for (int s = 0; s < 4; ++s) {
;         const bf16x8 pf = pack8(S[s >> 1], s & 1);
; #pragma unroll
;         for (int dt = 0; dt < 2; ++dt) O[dt] = MFMA(vf[2 * s + dt], pf, O[dt]);
;     }
; }
; template <int KIND>
; DI void attn_unit(const Params& p, int l, int b, int head, int qt, int qcol, int kcol, int vfeat, int gcol, int mixcol,
;                   int t1, int n1, int t2, int n2, char* smem) {
;     ...
;             } else {
;                 f32x16 S[2];
; #pragma unroll
;                 for (int t = 0; t < 2; ++t) S[t] = MFMA(kf[t], qf[0], cz);
; #pragma unroll
;                 for (int s = 1; s < 4; ++s)
; #pragma unroll
;                     for (int t = 0; t < 2; ++t) S[t] = MFMA(kf[2 * s + t], qf[s], S[t]);
;                 LOAD_VF();
;                 if (KIND == 2 && tile < 32) {
;                     const char* brow = smem + ATT_BIAS + (tile - nrow + 7) * 128;
; #pragma unroll
;                     for (int t = 0; t < 2; ++t)
; #pragma unroll
;                         for (int e = 0; e < 16; ++e) S[t][e] += *(const float*)(brow + bcol[t][e]);
;                 }
;                 softmax_tile(S, l0);
;                 pv_tile(S, O0, vf);
;             }
.LBB0_104:
	v_lshl_add_u32 v52, s35, 14, v108
	v_add_u32_e32 v109, v52, v107
	v_add_u32_e32 v138, v52, v106
	v_add_u32_e32 v139, v52, v103
	v_add_u32_e32 v140, v52, v101
	s_waitcnt vmcnt(4)
	s_barrier
	ds_read_b128 v[48:51], v109
	ds_read_b128 v[110:113], v109 offset:4096
	ds_read_b128 v[114:117], v138
	ds_read_b128 v[118:121], v138 offset:4096
	ds_read_b128 v[122:125], v139
	ds_read_b128 v[126:129], v139 offset:4096
	ds_read_b128 v[130:133], v140
	ds_read_b128 v[134:137], v140 offset:4096
	v_lshl_add_u32 v60, s34, 14, v100
	v_lshl_add_u64 v[56:57], v[98:99], 0, s[4:5]
	v_add_u32_e32 v63, 0x1000, v60
	v_readfirstlane_b32 s42, v60
	v_add_u32_e32 v62, 0x2000, v60
	v_lshl_add_u64 v[58:59], v[56:57], 0, s[92:93]
	s_mov_b32 m0, s42
	v_readfirstlane_b32 s42, v63
	v_lshl_add_u64 v[52:53], v[96:97], 0, s[4:5]
	v_add_u32_e32 v61, 0x3000, v60
	v_lshl_add_u64 v[56:57], v[56:57], 0, s[94:95]
	global_load_lds_dwordx4 v[58:59], off
	s_mov_b32 m0, s42
	v_readfirstlane_b32 s42, v62
	v_lshl_add_u64 v[54:55], v[52:53], 0, s[92:93]
	global_load_lds_dwordx4 v[56:57], off
	s_mov_b32 m0, s42
	v_readfirstlane_b32 s42, v61
	v_lshl_add_u64 v[52:53], v[52:53], 0, s[94:95]
	global_load_lds_dwordx4 v[54:55], off
	s_mov_b32 m0, s42
	s_add_i32 s42, s35, 1
	global_load_lds_dwordx4 v[52:53], off
	s_cmp_lg_u32 s35, 2
	s_cselect_b32 s35, s42, 0
	s_add_i32 s42, s34, 1
	s_waitcnt lgkmcnt(0)
	v_mfma_f32_32x32x16_bf16 v[64:79], v[48:51], v[92:95], v[16:31]
	v_mfma_f32_32x32x16_bf16 v[48:63], v[110:113], v[92:95], v[16:31]
	v_mfma_f32_32x32x16_bf16 v[64:79], v[114:117], v[88:91], v[64:79]
	v_mfma_f32_32x32x16_bf16 v[48:63], v[118:121], v[88:91], v[48:63]
	v_mfma_f32_32x32x16_bf16 v[64:79], v[122:125], v[84:87], v[64:79]
	v_mfma_f32_32x32x16_bf16 v[48:63], v[126:129], v[84:87], v[48:63]
	v_mfma_f32_32x32x16_bf16 v[64:79], v[130:133], v[80:83], v[64:79]
	v_mfma_f32_32x32x16_bf16 v[48:63], v[134:137], v[80:83], v[48:63]
	ds_read_b128 v[110:113], v109 offset:8192
	ds_read_b128 v[114:117], v109 offset:12288
	ds_read_b128 v[118:121], v138 offset:8192
	ds_read_b128 v[122:125], v138 offset:12288
	ds_read_b128 v[126:129], v139 offset:8192
	ds_read_b128 v[130:133], v139 offset:12288
	ds_read_b128 v[134:137], v140 offset:8192
	ds_read_b128 v[138:141], v140 offset:12288
	s_cmp_lg_u32 s34, 2
	s_cselect_b32 s34, s42, 0
	s_nop 0
	v_exp_f32_e32 v64, v64
	v_exp_f32_e32 v65, v65
	v_exp_f32_e32 v66, v66
	v_exp_f32_e32 v67, v67
	v_exp_f32_e32 v68, v68
	v_exp_f32_e32 v69, v69
	v_exp_f32_e32 v70, v70
	v_exp_f32_e32 v71, v71
	v_add_f32_e64 v142, v64, 0
	v_add_f32_e64 v143, v65, 0
	v_cvt_pk_bf16_f32 v64, v64, v65
	v_add_f32_e64 v142, v66, v142
	v_add_f32_e64 v143, v67, v143
	v_cvt_pk_bf16_f32 v65, v66, v67
	v_cvt_pk_bf16_f32 v66, v68, v69
	v_cvt_pk_bf16_f32 v67, v70, v71
	v_add_f32_e64 v142, v68, v142
	v_add_f32_e64 v143, v69, v143
	v_exp_f32_e32 v72, v72
	s_waitcnt lgkmcnt(0)
	v_mfma_f32_32x32x16_bf16 v[32:47], v[110:113], v[64:67], v[32:47]
	v_add_f32_e64 v142, v70, v142
	v_add_f32_e64 v143, v71, v143
	v_exp_f32_e32 v73, v73
	v_exp_f32_e32 v74, v74
	v_exp_f32_e32 v75, v75
	v_exp_f32_e32 v70, v76
	v_exp_f32_e32 v71, v77
	v_exp_f32_e32 v76, v78
	v_mfma_f32_32x32x16_bf16 v[0:15], v[114:117], v[64:67], v[0:15]
	v_exp_f32_e32 v77, v79
	v_exp_f32_e32 v78, v48
	v_exp_f32_e32 v79, v49
	v_exp_f32_e32 v64, v50
	v_exp_f32_e32 v65, v51
	v_cvt_pk_bf16_f32 v48, v72, v73
	v_cvt_pk_bf16_f32 v49, v74, v75
	v_cvt_pk_bf16_f32 v50, v70, v71
	v_cvt_pk_bf16_f32 v51, v76, v77
	v_exp_f32_e32 v52, v52
	v_exp_f32_e32 v53, v53
	v_mfma_f32_32x32x16_bf16 v[32:47], v[118:121], v[48:51], v[32:47]
	v_exp_f32_e32 v54, v54
	v_exp_f32_e32 v55, v55
	v_add_f32_e64 v68, v72, v142
	v_add_f32_e64 v69, v73, v143
	v_exp_f32_e32 v56, v56
	v_add_f32_e64 v68, v74, v68
	v_add_f32_e64 v69, v75, v69
	v_exp_f32_e32 v57, v57
	v_add_f32_e64 v66, v70, v68
	v_add_f32_e64 v67, v71, v69
	v_mfma_f32_32x32x16_bf16 v[0:15], v[122:125], v[48:51], v[0:15]
	v_add_f32_e64 v66, v76, v66
	v_add_f32_e64 v67, v77, v67
	v_cvt_pk_bf16_f32 v48, v78, v79
	v_cvt_pk_bf16_f32 v49, v64, v65
	v_cvt_pk_bf16_f32 v50, v52, v53
	v_cvt_pk_bf16_f32 v51, v54, v55
	v_add_f32_e64 v66, v78, v66
	v_add_f32_e64 v67, v79, v67
	v_exp_f32_e32 v58, v58
	v_mfma_f32_32x32x16_bf16 v[32:47], v[126:129], v[48:51], v[32:47]
	v_add_f32_e64 v66, v64, v66
	v_add_f32_e64 v67, v65, v67
	v_exp_f32_e32 v59, v59
	v_add_f32_e64 v52, v52, v66
	v_add_f32_e64 v53, v53, v67
	s_add_u32 s4, s4, 0x2000
	v_add_f32_e64 v52, v54, v52
	v_add_f32_e64 v53, v55, v53
	v_exp_f32_e32 v54, v60
	v_exp_f32_e32 v55, v61
	v_mfma_f32_32x32x16_bf16 v[0:15], v[130:133], v[48:51], v[0:15]
	v_exp_f32_e32 v60, v62
	v_exp_f32_e32 v61, v63
	v_cvt_pk_bf16_f32 v48, v56, v57
	v_cvt_pk_bf16_f32 v49, v58, v59
	v_cvt_pk_bf16_f32 v50, v54, v55
	v_cvt_pk_bf16_f32 v51, v60, v61
	v_add_f32_e64 v52, v56, v52
	v_add_f32_e64 v53, v57, v53
	s_addc_u32 s5, s5, 0
	v_mfma_f32_32x32x16_bf16 v[32:47], v[134:137], v[48:51], v[32:47]
	v_add_f32_e64 v52, v58, v52
	v_add_f32_e64 v53, v59, v53
	s_cmp_eq_u32 s44, s4
	v_add_f32_e64 v52, v54, v52
	v_add_f32_e64 v53, v55, v53
	v_add_f32_e64 v52, v60, v52
	v_add_f32_e64 v53, v61, v53
	s_nop 0
	v_add_f32_e32 v52, v52, v53
	v_mfma_f32_32x32x16_bf16 v[0:15], v[138:141], v[48:51], v[0:15]
	v_add_f32_e32 v104, v104, v52
	s_cbranch_scc0 .LBB0_104
	s_lshl_b32 s4, s35, 14
	s_add_i32 s5, s4, 32
	v_add_u32_e32 v52, s5, v105
	v_add_u32_e32 v100, v52, v107
	v_add_u32_e32 v132, v52, v106
	v_add_u32_e32 v133, v52, v103
	v_add_u32_e32 v134, v52, v101
	s_waitcnt vmcnt(4)
	s_barrier
; #define MFMA(a, b, c) __builtin_amdgcn_mfma_f32_32x32x16_bf16((a), (b), (c), 0, 0, 0)
; #define LOAD_VF() do { \
;             __builtin_amdgcn_sched_barrier(0); \
;             _Pragma("unroll") for (int s = 0; s < 4; ++s) \
;                 _Pragma("unroll") for (int dt = 0; dt < 2; ++dt) vf[2 * s + dt] = ldv_frag(sv, 32 * dt + r, 2 * s + h, xr); \
;             __builtin_amdgcn_sched_barrier(0); } while (0)
; DI void softmax_tile(f32x16 (&S)[2], float& lsum) {
;     f2_t ps = {0.f, 0.f};
; #pragma unroll
;     for (int t = 0; t < 2; ++t)
; #pragma unroll
;         for (int e = 0; e < 16; e += 2) {
;             f2_t pv; pv.x = __builtin_amdgcn_exp2f(S[t][e]); pv.y = __builtin_amdgcn_exp2f(S[t][e + 1]);
;             S[t][e] = pv.x; S[t][e + 1] = pv.y;
;             ps += pv;
;         }
;     lsum += ps.x + ps.y;
; }
; DI void pv_tile(const f32x16 (&S)[2], f32x16 (&O)[2], const bf16x8 (&vf)[8]) {
; #pragma unroll
;     for (int s = 0; s < 4; ++s) {
;         const bf16x8 pf = pack8(S[s >> 1], s & 1);
; #pragma unroll
;         for (int dt = 0; dt < 2; ++dt) O[dt] = MFMA(vf[2 * s + dt], pf, O[dt]);
;     }
; }
; template <int KIND>
; DI void attn_unit(const Params& p, int l, int b, int head, int qt, int qcol, int kcol, int vfeat, int gcol, int mixcol,
;                   int t1, int n1, int t2, int n2, char* smem) {
;     ...
;             } else {
;                 f32x16 S[2];
; #pragma unroll
;                 for (int t = 0; t < 2; ++t) S[t] = MFMA(kf[t], qf[0], cz);
; #pragma unroll
;                 for (int s = 1; s < 4; ++s)
; #pragma unroll
;                     for (int t = 0; t < 2; ++t) S[t] = MFMA(kf[2 * s + t], qf[s], S[t]);
;                 LOAD_VF();
;                 if (KIND == 2 && tile < 32) {
;                     const char* brow = smem + ATT_BIAS + (tile - nrow + 7) * 128;
; #pragma unroll
;                     for (int t = 0; t < 2; ++t)
; #pragma unroll
;                         for (int e = 0; e < 16; ++e) S[t][e] += *(const float*)(brow + bcol[t][e]);
;                 }
;                 softmax_tile(S, l0);
;                 pv_tile(S, O0, vf);
;             }
	ds_read_b128 v[48:51], v100
	ds_read_b128 v[96:99], v100 offset:4096
	ds_read_b128 v[108:111], v132
	ds_read_b128 v[112:115], v132 offset:4096
	ds_read_b128 v[116:119], v133
	ds_read_b128 v[120:123], v133 offset:4096
	ds_read_b128 v[124:127], v134
	ds_read_b128 v[128:131], v134 offset:4096
	s_waitcnt lgkmcnt(0)
	v_mfma_f32_32x32x16_bf16 v[64:79], v[48:51], v[92:95], v[16:31]
	v_mfma_f32_32x32x16_bf16 v[48:63], v[96:99], v[92:95], v[16:31]
	v_mfma_f32_32x32x16_bf16 v[64:79], v[108:111], v[88:91], v[64:79]
	v_mfma_f32_32x32x16_bf16 v[48:63], v[112:115], v[88:91], v[48:63]
	v_mfma_f32_32x32x16_bf16 v[64:79], v[116:119], v[84:87], v[64:79]
	v_mfma_f32_32x32x16_bf16 v[48:63], v[120:123], v[84:87], v[48:63]
	v_mfma_f32_32x32x16_bf16 v[64:79], v[124:127], v[80:83], v[64:79]
	v_mfma_f32_32x32x16_bf16 v[48:63], v[128:131], v[80:83], v[48:63]
	ds_read_b128 v[96:99], v100 offset:8192
	ds_read_b128 v[108:111], v100 offset:12288
	ds_read_b128 v[112:115], v132 offset:8192
	ds_read_b128 v[116:119], v132 offset:12288
	ds_read_b128 v[120:123], v133 offset:8192
	ds_read_b128 v[124:127], v133 offset:12288
	ds_read_b128 v[128:131], v134 offset:8192
	ds_read_b128 v[132:135], v134 offset:12288
	s_nop 2
	v_exp_f32_e32 v64, v64
	v_exp_f32_e32 v65, v65
	v_exp_f32_e32 v66, v66
	v_exp_f32_e32 v67, v67
	v_exp_f32_e32 v68, v68
	v_exp_f32_e32 v69, v69
	v_exp_f32_e32 v70, v70
	v_exp_f32_e32 v71, v71
	v_add_f32_e64 v136, v64, 0
	v_add_f32_e64 v137, v65, 0
	v_exp_f32_e32 v72, v72
	v_add_f32_e64 v136, v66, v136
	v_add_f32_e64 v137, v67, v137
	v_exp_f32_e32 v73, v73
	v_cvt_pk_bf16_f32 v64, v64, v65
	v_cvt_pk_bf16_f32 v65, v66, v67
	v_cvt_pk_bf16_f32 v66, v68, v69
	v_cvt_pk_bf16_f32 v67, v70, v71
	v_exp_f32_e32 v74, v74
	v_exp_f32_e32 v75, v75
	s_waitcnt lgkmcnt(0)
	v_mfma_f32_32x32x16_bf16 v[32:47], v[96:99], v[64:67], v[32:47]
	v_add_f32_e64 v136, v68, v136
	v_add_f32_e64 v137, v69, v137
	v_exp_f32_e32 v68, v76
	v_exp_f32_e32 v69, v77
	v_add_f32_e64 v136, v70, v136
	v_add_f32_e64 v137, v71, v137
	v_exp_f32_e32 v70, v78
	v_exp_f32_e32 v71, v79
	v_add_f32_e64 v136, v72, v136
	v_add_f32_e64 v137, v73, v137
	v_mfma_f32_32x32x16_bf16 v[0:15], v[108:111], v[64:67], v[0:15]
	v_exp_f32_e32 v48, v48
	v_exp_f32_e32 v49, v49
	v_add_f32_e64 v136, v74, v136
	v_add_f32_e64 v137, v75, v137
	v_exp_f32_e32 v50, v50
	v_add_f32_e64 v76, v68, v136
	v_add_f32_e64 v77, v69, v137
	v_cvt_pk_bf16_f32 v66, v68, v69
	v_add_f32_e64 v64, v70, v76
	v_add_f32_e64 v65, v71, v77
	v_cvt_pk_bf16_f32 v67, v70, v71
	v_add_f32_e64 v76, v48, v64
	v_add_f32_e64 v77, v49, v65
	v_cvt_pk_bf16_f32 v64, v72, v73
	v_cvt_pk_bf16_f32 v65, v74, v75
	v_exp_f32_e32 v51, v51
	v_exp_f32_e32 v52, v52
	v_mfma_f32_32x32x16_bf16 v[32:47], v[112:115], v[64:67], v[32:47]
	v_exp_f32_e32 v53, v53
	v_exp_f32_e32 v54, v54
	v_exp_f32_e32 v55, v55
	v_add_f32_e64 v68, v50, v76
	v_add_f32_e64 v69, v51, v77
	v_exp_f32_e32 v56, v56
	v_add_f32_e64 v68, v52, v68
	v_add_f32_e64 v69, v53, v69
	v_exp_f32_e32 v57, v57
	v_mfma_f32_32x32x16_bf16 v[0:15], v[116:119], v[64:67], v[0:15]
	v_add_f32_e64 v64, v54, v68
	v_add_f32_e64 v65, v55, v69
	v_cvt_pk_bf16_f32 v48, v48, v49
	v_cvt_pk_bf16_f32 v49, v50, v51
	v_cvt_pk_bf16_f32 v51, v54, v55
	v_exp_f32_e32 v54, v58
	v_exp_f32_e32 v55, v59
	s_addk_i32 s4, 0x4000
	s_cmp_lg_u32 s35, 2
	v_cvt_pk_bf16_f32 v50, v52, v53
	s_cselect_b32 s4, s4, 0
	v_add_f32_e64 v52, v56, v64
	v_add_f32_e64 v53, v57, v65
	v_mfma_f32_32x32x16_bf16 v[32:47], v[120:123], v[48:51], v[32:47]
	s_add_i32 s4, s4, 32
	v_exp_f32_e32 v58, v60
	v_exp_f32_e32 v59, v61
	v_exp_f32_e32 v60, v62
	v_exp_f32_e32 v61, v63
	s_waitcnt vmcnt(0)
	s_barrier
	v_mfma_f32_32x32x16_bf16 v[0:15], v[124:127], v[48:51], v[0:15]
	v_add_f32_e64 v48, v54, v52
	v_add_f32_e64 v49, v55, v53
	v_add_u32_e32 v52, s4, v105
	v_add_u32_e32 v105, v52, v107
	v_add_u32_e32 v118, v52, v106
	v_add_u32_e32 v103, v52, v103
	v_add_u32_e32 v119, v52, v101
	ds_read_b128 v[64:67], v105
	ds_read_b128 v[68:71], v105 offset:4096
	ds_read_b128 v[72:75], v118
	ds_read_b128 v[76:79], v118 offset:4096
	ds_read_b128 v[106:109], v103
	ds_read_b128 v[110:113], v103 offset:4096
	ds_read_b128 v[98:101], v119
	ds_read_b128 v[114:117], v119 offset:4096
	v_add_f32_e64 v48, v58, v48
	v_add_f32_e64 v49, v59, v49
	v_cvt_pk_bf16_f32 v50, v58, v59
	v_add_f32_e64 v96, v60, v48
	v_add_f32_e64 v97, v61, v49
	v_cvt_pk_bf16_f32 v48, v56, v57
	v_cvt_pk_bf16_f32 v49, v54, v55
	v_cvt_pk_bf16_f32 v51, v60, v61
	s_nop 1
	v_mfma_f32_32x32x16_bf16 v[32:47], v[128:131], v[48:51], v[32:47]
	v_mfma_f32_32x32x16_bf16 v[0:15], v[132:135], v[48:51], v[0:15]
	s_waitcnt lgkmcnt(0)
; #define MFMA(a, b, c) __builtin_amdgcn_mfma_f32_32x32x16_bf16((a), (b), (c), 0, 0, 0)
; DI int otid() { int t = threadIdx.x; asm volatile("" : "+v"(t)); return t; }
; DI void softmax_tile(f32x16 (&S)[2], float& lsum) {
;     f2_t ps = {0.f, 0.f};
; #pragma unroll
;     for (int t = 0; t < 2; ++t)
; #pragma unroll
;         for (int e = 0; e < 16; e += 2) {
;             f2_t pv; pv.x = __builtin_amdgcn_exp2f(S[t][e]); pv.y = __builtin_amdgcn_exp2f(S[t][e + 1]);
;             S[t][e] = pv.x; S[t][e + 1] = pv.y;
;             ps += pv;
;         }
;     lsum += ps.x + ps.y;
; }
; DI void pv_tile(const f32x16 (&S)[2], f32x16 (&O)[2], const bf16x8 (&vf)[8]) {
; #pragma unroll
;     for (int s = 0; s < 4; ++s) {
;         const bf16x8 pf = pack8(S[s >> 1], s & 1);
; #pragma unroll
;         for (int dt = 0; dt < 2; ++dt) O[dt] = MFMA(vf[2 * s + dt], pf, O[dt]);
;     }
; }
; template <int KIND>
; DI void attn_unit(const Params& p, int l, int b, int head, int qt, int qcol, int kcol, int vfeat, int gcol, int mixcol,
;                   int t1, int n1, int t2, int n2, char* smem) {
;     ...
;             } else {
;                 f32x16 S[2];
; #pragma unroll
;                 for (int t = 0; t < 2; ++t) S[t] = MFMA(kf[t], qf[0], cz);
; #pragma unroll
;                 for (int s = 1; s < 4; ++s)
; #pragma unroll
;                     for (int t = 0; t < 2; ++t) S[t] = MFMA(kf[2 * s + t], qf[s], S[t]);
;                 LOAD_VF();
;                 if (KIND == 2 && tile < 32) {
;                     const char* brow = smem + ATT_BIAS + (tile - nrow + 7) * 128;
; #pragma unroll
;                     for (int t = 0; t < 2; ++t)
; #pragma unroll
;                         for (int e = 0; e < 16; ++e) S[t][e] += *(const float*)(brow + bcol[t][e]);
;                 }
;                 softmax_tile(S, l0);
;                 pv_tile(S, O0, vf);
;             }
;     ...
;         }
;     }
;     l0 = xsum32(l0);
;     const float inv0 = 1.f / l0;
;     const int tid_e = otid();
;     const size_t qrow_e = (size_t)b * TPB + qt * 128 + 32 * (tid_e >> 6) + (tid_e & 31);
;     bf16_t* orow = p.hmix + ((size_t)(mixcol >> 5) * NTOK + qrow_e) * 32;
;     const bf16_t* grow = p.qkv + ((size_t)(gcol >> 6) * NTOK + qrow_e) * 64;
	v_mfma_f32_32x32x16_bf16 v[48:63], v[64:67], v[92:95], v[16:31]
	v_mfma_f32_32x32x16_bf16 v[16:31], v[68:71], v[92:95], v[16:31]
	v_mfma_f32_32x32x16_bf16 v[48:63], v[72:75], v[88:91], v[48:63]
	v_mfma_f32_32x32x16_bf16 v[16:31], v[76:79], v[88:91], v[16:31]
	v_mfma_f32_32x32x16_bf16 v[48:63], v[106:109], v[84:87], v[48:63]
	v_mfma_f32_32x32x16_bf16 v[16:31], v[110:113], v[84:87], v[16:31]
	v_mfma_f32_32x32x16_bf16 v[48:63], v[98:101], v[80:83], v[48:63]
	v_mfma_f32_32x32x16_bf16 v[16:31], v[114:117], v[80:83], v[16:31]
	ds_read_b128 v[92:95], v105 offset:8192
	ds_read_b128 v[76:79], v105 offset:12288
	ds_read_b128 v[88:91], v118 offset:8192
	ds_read_b128 v[72:75], v118 offset:12288
	ds_read_b128 v[84:87], v103 offset:8192
	ds_read_b128 v[68:71], v103 offset:12288
	ds_read_b128 v[80:83], v119 offset:8192
	ds_read_b128 v[64:67], v119 offset:12288
	s_nop 2
	v_exp_f32_e32 v98, v48
	v_exp_f32_e32 v99, v49
	v_exp_f32_e32 v50, v50
	v_exp_f32_e32 v51, v51
	v_exp_f32_e32 v52, v52
	v_exp_f32_e32 v53, v53
	v_exp_f32_e32 v54, v54
	v_exp_f32_e32 v55, v55
	v_add_f32_e64 v48, v98, 0
	v_add_f32_e64 v49, v99, 0
	v_exp_f32_e32 v56, v56
	v_exp_f32_e32 v57, v57
	v_add_f32_e64 v48, v50, v48
	v_add_f32_e64 v49, v51, v49
	v_mov_b32_e32 v103, v200
	v_add_f32_e64 v48, v52, v48
	v_add_f32_e64 v49, v53, v49
	s_add_u32 s4, s29, s6
	v_add_f32_e64 v48, v54, v48
	v_add_f32_e64 v49, v55, v49
	s_addc_u32 s5, s7, 0
	v_add_f32_e64 v100, v56, v48
	v_add_f32_e64 v101, v57, v49
	v_ashrrev_i32_e32 v48, 1, v103
	v_and_b32_e32 v48, 0xffffffe0, v48
	v_ashrrev_i32_e32 v49, 31, v48
	v_and_or_b32 v106, v103, 31, s4
	v_mov_b32_e32 v107, s5
	s_lshr_b32 s4, s9, 6
	v_lshl_add_u64 v[106:107], v[106:107], 0, v[48:49]
	s_mulk_i32 s4, 0x4800
	s_mov_b32 s5, s75
	v_lshl_add_u64 v[48:49], v[106:107], 0, s[4:5]
	v_lshlrev_b64 v[48:49], 7, v[48:49]
	v_lshl_add_u64 v[48:49], s[40:41], 0, v[48:49]
	v_lshlrev_b32_e32 v192, 3, v102
	v_lshl_add_u64 v[48:49], v[48:49], 0, v[192:193]
	global_load_dwordx2 v[102:103], v[48:49], off
	v_exp_f32_e32 v58, v58
	v_exp_f32_e32 v59, v59
	v_exp_f32_e32 v60, v60
	v_exp_f32_e32 v61, v61
	v_exp_f32_e32 v62, v62
	v_exp_f32_e32 v63, v63
	v_exp_f32_e32 v114, v28
	v_exp_f32_e32 v115, v29
	v_exp_f32_e32 v116, v30
	v_exp_f32_e32 v117, v31
	v_cvt_pk_bf16_f32 v28, v98, v99
	v_cvt_pk_bf16_f32 v29, v50, v51
	v_cvt_pk_bf16_f32 v30, v52, v53
	v_cvt_pk_bf16_f32 v31, v54, v55
	v_exp_f32_e32 v16, v16
	v_exp_f32_e32 v17, v17
	s_waitcnt lgkmcnt(0)
	v_mfma_f32_32x32x16_bf16 v[32:47], v[92:95], v[28:31], v[32:47]
	v_add_f32_e64 v100, v58, v100
	v_add_f32_e64 v101, v59, v101
	v_exp_f32_e32 v18, v18
	v_exp_f32_e32 v19, v19
	v_add_f32_e64 v100, v60, v100
	v_add_f32_e64 v101, v61, v101
	v_exp_f32_e32 v108, v20
	v_exp_f32_e32 v109, v21
	v_add_f32_e64 v100, v62, v100
	v_add_f32_e64 v101, v63, v101
	v_exp_f32_e32 v110, v22
	v_exp_f32_e32 v111, v23
	v_add_f32_e64 v20, v16, v100
	v_add_f32_e64 v21, v17, v101
	v_exp_f32_e32 v100, v24
	v_exp_f32_e32 v101, v25
	v_add_f32_e64 v20, v18, v20
	v_add_f32_e64 v21, v19, v21
	v_exp_f32_e32 v112, v26
	v_exp_f32_e32 v113, v27
	v_add_f32_e64 v20, v108, v20
	v_add_f32_e64 v21, v109, v21
	v_cvt_pk_bf16_f32 v24, v56, v57
	v_add_f32_e64 v20, v110, v20
	v_add_f32_e64 v21, v111, v21
	v_cvt_pk_bf16_f32 v25, v58, v59
	v_cvt_pk_bf16_f32 v26, v60, v61
	v_cvt_pk_bf16_f32 v27, v62, v63
	v_add_f32_e64 v20, v100, v20
	v_add_f32_e64 v21, v101, v21
	v_mov_b32_e32 v22, v96
	v_mfma_f32_32x32x16_bf16 v[32:47], v[88:91], v[24:27], v[32:47]
	v_add_f32_e64 v20, v112, v20
	v_add_f32_e64 v21, v113, v21
	s_lshr_b32 s6, s8, 5
	v_add_f32_e64 v20, v114, v20
	v_add_f32_e64 v21, v115, v21
	s_mulk_i32 s6, 0x4800
	v_add_f32_e64 v20, v116, v20
	v_add_f32_e64 v21, v117, v21
	s_ashr_i32 s7, s6, 31
	v_mov_b32_e32 v23, v20
	v_mov_b32_e32 v20, v97
	v_add_f32_e64 v20, v22, v20
	v_add_f32_e64 v21, v23, v21
	v_cvt_pk_bf16_f32 v22, v108, v109
	v_add_f32_e32 v20, v104, v20
	v_add_f32_e32 v50, v20, v21
	v_cvt_pk_bf16_f32 v20, v16, v17
	v_cvt_pk_bf16_f32 v21, v18, v19
	v_cvt_pk_bf16_f32 v23, v110, v111
	v_mov_b32_e32 v18, v50
	s_nop 1
	v_permlane32_swap_b32_e32 v50, v18
	v_mfma_f32_32x32x16_bf16 v[32:47], v[84:87], v[20:23], v[32:47]
	v_add_f32_e32 v50, v50, v18
	v_div_scale_f32 v51, s[4:5], v50, v50, 1.0
	v_rcp_f32_e32 v52, v51
	v_cvt_pk_bf16_f32 v16, v100, v101
	v_cvt_pk_bf16_f32 v17, v112, v113
	v_cvt_pk_bf16_f32 v18, v114, v115
	v_cvt_pk_bf16_f32 v19, v116, v117
	v_fma_f32 v53, -v51, v52, 1.0
	v_fmac_f32_e32 v52, v53, v52
	v_mfma_f32_32x32x16_bf16 v[32:47], v[80:83], v[16:19], v[32:47]
	v_div_scale_f32 v53, vcc, 1.0, v50, 1.0
	v_mul_f32_e32 v54, v53, v52
	v_fma_f32 v55, -v51, v54, v53
	v_fmac_f32_e32 v54, v55, v52
	s_load_dwordx2 s[4:5], s[0:1], 0xb8
	v_fma_f32 v51, -v51, v54, v53
	v_div_fmas_f32 v51, v51, v52, v54
	v_div_fixup_f32 v50, v51, v50, 1.0
	v_lshl_add_u64 v[52:53], v[106:107], 0, s[6:7]
	v_lshlrev_b64 v[52:53], 6, v[52:53]
	s_waitcnt vmcnt(0)
; DI unsigned pk2(float a, float b) { f2_t v = {a, b}; bf2_t r = __builtin_convertvector(v, bf2_t); return __builtin_bit_cast(unsigned, r); }
; DI float bf2f(bf16_t v) { return __uint_as_float(((unsigned)v) << 16); }
; template <int KIND>
; DI void attn_unit(const Params& p, int l, int b, int head, int qt, int qcol, int kcol, int vfeat, int gcol, int mixcol,
;                   int t1, int n1, int t2, int n2, char* smem) {
;     ...
;     } else {
; #pragma unroll
;         for (int t = 0; t < 2; ++t)
; #pragma unroll
;             for (int q = 0; q < 4; ++q) {
;                 const int f = 32 * t + 8 * q + 4 * h;
;                 const uint2 gg = *(const uint2*)(grow + f);
;                 const float g0 = bf2f((bf16_t)(gg.x & 0xffff)), g1 = bf2f((bf16_t)(gg.x >> 16)), g2 = bf2f((bf16_t)(gg.y & 0xffff)), g3 = bf2f((bf16_t)(gg.y >> 16));
;                 uint2 o;
;                 o.x = pk2(O0[t][4 * q + 0] * inv0 * g0, O0[t][4 * q + 1] * inv0 * g1);
;                 o.y = pk2(O0[t][4 * q + 2] * inv0 * g2, O0[t][4 * q + 3] * inv0 * g3);
;                 *(uint2*)(orow + (size_t)t * NTOK * 32 + 8 * q + 4 * h) = o;
;             }
;     }
	v_lshlrev_b32_e32 v54, 16, v102
	v_and_b32_e32 v55, 0xffff0000, v102
	v_lshlrev_b32_e32 v56, 16, v103
	v_and_b32_e32 v57, 0xffff0000, v103
	v_pk_mul_f32 v[32:33], v[32:33], v[50:51] op_sel_hi:[1,0]
	v_pk_mul_f32 v[34:35], v[34:35], v[50:51] op_sel_hi:[1,0]
	s_waitcnt lgkmcnt(0)
	v_lshl_add_u64 v[52:53], s[4:5], 0, v[52:53]
	v_pk_mul_f32 v[32:33], v[32:33], v[54:55]
	v_pk_mul_f32 v[34:35], v[34:35], v[56:57]
	v_lshl_add_u64 v[52:53], v[52:53], 0, v[192:193]
	v_cvt_pk_bf16_f32 v32, v32, v33
	v_cvt_pk_bf16_f32 v33, v34, v35
	global_store_dwordx2 v[52:53], v[32:33], off
	global_load_dwordx2 v[32:33], v[48:49], off offset:16
	v_mfma_f32_32x32x16_bf16 v[0:15], v[76:79], v[28:31], v[0:15]
	v_mul_f32_e64 v28, v36, v50
	v_mul_f32_e64 v29, v37, v50
	v_mul_f32_e64 v30, v38, v50
	v_mul_f32_e64 v31, v39, v50
	s_mov_b32 s4, 0x120000
	s_waitcnt vmcnt(0)
	v_lshlrev_b32_e32 v34, 16, v32
	v_and_b32_e32 v35, 0xffff0000, v32
	v_lshlrev_b32_e32 v32, 16, v33
	v_and_b32_e32 v33, 0xffff0000, v33
	v_pk_mul_f32 v[28:29], v[28:29], v[34:35]
	v_pk_mul_f32 v[30:31], v[30:31], v[32:33]
	v_cvt_pk_bf16_f32 v28, v28, v29
	v_cvt_pk_bf16_f32 v29, v30, v31
	global_store_dwordx2 v[52:53], v[28:29], off offset:16
	global_load_dwordx2 v[28:29], v[48:49], off offset:32
	v_mfma_f32_32x32x16_bf16 v[0:15], v[72:75], v[24:27], v[0:15]
	v_mul_f32_e64 v24, v40, v50
	v_mul_f32_e64 v25, v41, v50
	v_mul_f32_e64 v26, v42, v50
	v_mul_f32_e64 v27, v43, v50
	s_waitcnt vmcnt(0)
	v_lshlrev_b32_e32 v30, 16, v28
	v_and_b32_e32 v31, 0xffff0000, v28
	v_lshlrev_b32_e32 v28, 16, v29
	v_and_b32_e32 v29, 0xffff0000, v29
	v_pk_mul_f32 v[24:25], v[24:25], v[30:31]
	v_pk_mul_f32 v[26:27], v[26:27], v[28:29]
	v_cvt_pk_bf16_f32 v24, v24, v25
	v_cvt_pk_bf16_f32 v25, v26, v27
	global_store_dwordx2 v[52:53], v[24:25], off offset:32
	global_load_dwordx2 v[24:25], v[48:49], off offset:48
	v_mfma_f32_32x32x16_bf16 v[0:15], v[68:71], v[20:23], v[0:15]
	v_mul_f32_e64 v20, v44, v50
	v_mul_f32_e64 v21, v45, v50
	v_mul_f32_e64 v22, v46, v50
	v_mul_f32_e64 v23, v47, v50
	s_waitcnt vmcnt(0)
	v_lshlrev_b32_e32 v26, 16, v24
	v_and_b32_e32 v27, 0xffff0000, v24
	v_lshlrev_b32_e32 v24, 16, v25
	v_and_b32_e32 v25, 0xffff0000, v25
	v_pk_mul_f32 v[20:21], v[20:21], v[26:27]
	v_pk_mul_f32 v[22:23], v[22:23], v[24:25]
	v_cvt_pk_bf16_f32 v20, v20, v21
	v_cvt_pk_bf16_f32 v21, v22, v23
	global_store_dwordx2 v[52:53], v[20:21], off offset:48
	global_load_dwordx2 v[20:21], v[48:49], off offset:64
	v_mfma_f32_32x32x16_bf16 v[0:15], v[64:67], v[16:19], v[0:15]
	v_add_co_u32_e32 v22, vcc, s4, v52
	s_mov_b64 s[4:5], 0
	s_nop 0
	v_addc_co_u32_e32 v23, vcc, 0, v53, vcc
	s_waitcnt vmcnt(0)
	v_lshlrev_b32_e32 v16, 16, v20
	s_nop 5
	v_pk_mul_f32 v[0:1], v[0:1], v[50:51] op_sel_hi:[1,0]
	v_pk_mul_f32 v[2:3], v[2:3], v[50:51] op_sel_hi:[1,0]
	v_and_b32_e32 v17, 0xffff0000, v20
	v_lshlrev_b32_e32 v18, 16, v21
	v_and_b32_e32 v19, 0xffff0000, v21
	v_pk_mul_f32 v[0:1], v[0:1], v[16:17]
	v_pk_mul_f32 v[2:3], v[2:3], v[18:19]
	v_cvt_pk_bf16_f32 v0, v0, v1
	v_cvt_pk_bf16_f32 v1, v2, v3
	global_store_dwordx2 v[22:23], v[0:1], off
	global_load_dwordx2 v[0:1], v[48:49], off offset:80
	v_pk_mul_f32 v[2:3], v[4:5], v[50:51] op_sel_hi:[1,0]
	v_pk_mul_f32 v[4:5], v[6:7], v[50:51] op_sel_hi:[1,0]
	s_waitcnt vmcnt(0)
	v_lshlrev_b32_e32 v6, 16, v0
	v_and_b32_e32 v7, 0xffff0000, v0
	v_lshlrev_b32_e32 v0, 16, v1
	v_and_b32_e32 v1, 0xffff0000, v1
	v_pk_mul_f32 v[2:3], v[2:3], v[6:7]
	v_pk_mul_f32 v[0:1], v[4:5], v[0:1]
	v_cvt_pk_bf16_f32 v2, v2, v3
	v_cvt_pk_bf16_f32 v3, v0, v1
	global_store_dwordx2 v[22:23], v[2:3], off offset:16
	global_load_dwordx2 v[0:1], v[48:49], off offset:96
	v_pk_mul_f32 v[2:3], v[8:9], v[50:51] op_sel_hi:[1,0]
	v_pk_mul_f32 v[4:5], v[10:11], v[50:51] op_sel_hi:[1,0]
	s_waitcnt vmcnt(0)
	v_lshlrev_b32_e32 v6, 16, v0
	v_and_b32_e32 v7, 0xffff0000, v0
	v_lshlrev_b32_e32 v0, 16, v1
	v_and_b32_e32 v1, 0xffff0000, v1
	v_pk_mul_f32 v[2:3], v[2:3], v[6:7]
	v_pk_mul_f32 v[0:1], v[4:5], v[0:1]
	v_cvt_pk_bf16_f32 v2, v2, v3
	v_cvt_pk_bf16_f32 v3, v0, v1
	global_store_dwordx2 v[22:23], v[2:3], off offset:32
	global_load_dwordx2 v[0:1], v[48:49], off offset:112
	v_pk_mul_f32 v[2:3], v[12:13], v[50:51] op_sel_hi:[1,0]
	v_pk_mul_f32 v[4:5], v[14:15], v[50:51] op_sel_hi:[1,0]
	s_waitcnt vmcnt(0)
	v_lshlrev_b32_e32 v6, 16, v0
	v_and_b32_e32 v7, 0xffff0000, v0
	v_lshlrev_b32_e32 v0, 16, v1
	v_and_b32_e32 v1, 0xffff0000, v1
	v_pk_mul_f32 v[2:3], v[2:3], v[6:7]
	v_pk_mul_f32 v[0:1], v[4:5], v[0:1]
	v_cvt_pk_bf16_f32 v2, v2, v3
	v_cvt_pk_bf16_f32 v3, v0, v1
	global_store_dwordx2 v[22:23], v[2:3], off offset:48
	s_branch .LBB0_85

; #define MFMA(a, b, c) __builtin_amdgcn_mfma_f32_32x32x16_bf16((a), (b), (c), 0, 0, 0)
; #define LOAD_VF() do { \
;             __builtin_amdgcn_sched_barrier(0); \
;             _Pragma("unroll") for (int s = 0; s < 4; ++s) \
;                 _Pragma("unroll") for (int dt = 0; dt < 2; ++dt) vf[2 * s + dt] = ldv_frag(sv, 32 * dt + r, 2 * s + h, xr); \
;             __builtin_amdgcn_sched_barrier(0); } while (0)
; template <int KIND>
; DI void attn_unit(const Params& p, int l, int b, int head, int qt, int qcol, int kcol, int vfeat, int gcol, int mixcol,
;                   int t1, int n1, int t2, int n2, char* smem) {
;     ...
;                 f32x16 S[2];
; #pragma unroll
;                 for (int t = 0; t < 2; ++t) S[t] = MFMA(kf[t], qf[0], cz);
; #pragma unroll
;                 for (int s = 1; s < 4; ++s)
; #pragma unroll
;                     for (int t = 0; t < 2; ++t) S[t] = MFMA(kf[2 * s + t], qf[s], S[t]);
;                 LOAD_VF();
;                 if (KIND == 2 && tile < 32) {
;                     const char* brow = smem + ATT_BIAS + (tile - nrow + 7) * 128;
; #pragma unroll
;                     for (int t = 0; t < 2; ++t)
; #pragma unroll
;                         for (int e = 0; e < 16; ++e) S[t][e] += *(const float*)(brow + bcol[t][e]);
;                 }
.LBB0_131:
	s_and_saveexec_b64 s[4:5], s[8:9]
	s_cbranch_execz .LBB0_135
	s_waitcnt lgkmcnt(0)
	v_mfma_f32_32x32x16_bf16 v[64:79], v[108:111], v[80:83], v[32:47]
	v_mfma_f32_32x32x16_bf16 v[48:63], v[104:107], v[80:83], v[32:47]
	v_mfma_f32_32x32x16_bf16 v[64:79], v[100:103], v[84:87], v[64:79]
	v_mfma_f32_32x32x16_bf16 v[48:63], v[96:99], v[84:87], v[48:63]
	v_mfma_f32_32x32x16_bf16 v[64:79], v[112:115], v[88:91], v[64:79]
	v_mfma_f32_32x32x16_bf16 v[48:63], v[116:119], v[88:91], v[48:63]
	v_mfma_f32_32x32x16_bf16 v[64:79], v[120:123], v[92:95], v[64:79]
	v_mfma_f32_32x32x16_bf16 v[48:63], v[124:127], v[92:95], v[48:63]
	ds_read_b128 v[156:159], v131 offset:8192
	ds_read_b128 v[152:155], v131 offset:12288
	ds_read_b128 v[148:151], v130 offset:8192
	ds_read_b128 v[144:147], v130 offset:12288
	ds_read_b128 v[140:143], v129 offset:8192
	ds_read_b128 v[136:139], v129 offset:12288
	ds_read_b128 v[132:135], v128 offset:8192
	ds_read_b128 v[128:131], v128 offset:12288
	s_andn2_b64 vcc, exec, s[6:7]
	s_cbranch_vccnz .LBB0_134
	v_sub_u32_e32 v222, s56, v214
	v_lshl_add_u32 v246, v222, 7, 32
	v_add_u32_e32 v222, v246, v166
	v_add_u32_e32 v223, v246, v167
	v_add_u32_e32 v224, v246, v168
	v_add_u32_e32 v225, v246, v169
	v_add_u32_e32 v226, v246, v170
	v_add_u32_e32 v227, v246, v171
	v_add_u32_e32 v228, v246, v172
	v_add_u32_e32 v229, v246, v173
	v_add_u32_e32 v230, v246, v174
	v_add_u32_e32 v231, v246, v175
	v_add_u32_e32 v232, v246, v176
	v_add_u32_e32 v233, v246, v177
	v_add_u32_e32 v234, v246, v178
	v_add_u32_e32 v235, v246, v180
	v_add_u32_e32 v236, v246, v181
	v_add_u32_e32 v237, v246, v182
	v_add_u32_e32 v238, v246, v183
	v_add_u32_e32 v239, v246, v184
	v_add_u32_e32 v240, v246, v185
	v_add_u32_e32 v241, v246, v186
	v_add_u32_e32 v242, v246, v187
	v_add_u32_e32 v243, v246, v188
	v_add_u32_e32 v244, v246, v189
	v_add_u32_e32 v245, v246, v190
	v_add_u32_e32 v247, v246, v191
	v_add_u32_e32 v248, v246, v192
	v_add_u32_e32 v249, v246, v194
	v_add_u32_e32 v250, v246, v195
	v_add_u32_e32 v251, v246, v196
	v_add_u32_e32 v252, v246, v197
	v_add_u32_e32 v253, v246, v198
	ds_read_b32 v222, v222 offset:50048
	ds_read_b32 v223, v223 offset:50048
	ds_read_b32 v224, v224 offset:50048
	ds_read_b32 v225, v225 offset:50048
	ds_read_b32 v226, v226 offset:50048
	ds_read_b32 v227, v227 offset:50048
	ds_read_b32 v228, v228 offset:50048
	ds_read_b32 v229, v229 offset:50048
	ds_read_b32 v230, v230 offset:50048
	ds_read_b32 v231, v231 offset:50048
	ds_read_b32 v232, v232 offset:50048
	ds_read_b32 v233, v233 offset:50048
	ds_read_b32 v234, v234 offset:50048
	ds_read_b32 v235, v235 offset:50048
	ds_read_b32 v236, v236 offset:50048
	ds_read_b32 v237, v237 offset:50048
	ds_read_b32 v238, v238 offset:50048
	ds_read_b32 v239, v239 offset:50048
	ds_read_b32 v240, v240 offset:50048
	ds_read_b32 v241, v241 offset:50048
	ds_read_b32 v242, v242 offset:50048
	ds_read_b32 v243, v243 offset:50048
	ds_read_b32 v244, v244 offset:50048
	ds_read_b32 v245, v245 offset:50048
	v_add_u32_e32 v210, v246, v199
	ds_read_b32 v246, v247 offset:50048
	ds_read_b32 v247, v248 offset:50048
	ds_read_b32 v248, v249 offset:50048
	ds_read_b32 v249, v250 offset:50048
	ds_read_b32 v250, v251 offset:50048
	ds_read_b32 v251, v252 offset:50048
	ds_read_b32 v252, v253 offset:50048
	ds_read_b32 v253, v210 offset:50048
	s_waitcnt lgkmcnt(0)
	v_add_f32_e64 v76, v76, v234
	v_add_f32_e64 v77, v77, v235
	v_add_f32_e64 v78, v78, v236
	v_add_f32_e64 v79, v79, v237
	v_add_f32_e64 v74, v74, v232
	v_add_f32_e64 v75, v75, v233
	v_add_f32_e64 v72, v72, v230
	v_add_f32_e64 v73, v73, v231
	v_add_f32_e64 v70, v70, v228
	v_add_f32_e64 v71, v71, v229
	v_add_f32_e64 v68, v68, v226
	v_add_f32_e64 v69, v69, v227
	v_add_f32_e64 v66, v66, v224
	v_add_f32_e64 v67, v67, v225
	v_add_f32_e64 v64, v64, v222
	v_add_f32_e64 v65, v65, v223
	v_add_f32_e64 v62, v62, v252
	v_add_f32_e64 v63, v63, v253
	v_add_f32_e64 v60, v60, v250
	v_add_f32_e64 v61, v61, v251
	v_add_f32_e64 v58, v58, v248
	v_add_f32_e64 v59, v59, v249
	v_add_f32_e64 v56, v56, v246
	v_add_f32_e64 v57, v57, v247
	v_add_f32_e64 v54, v54, v244
	v_add_f32_e64 v55, v55, v245
	v_add_f32_e64 v52, v52, v242
	v_add_f32_e64 v53, v53, v243
	v_add_f32_e64 v50, v50, v240
	v_add_f32_e64 v51, v51, v241
	v_add_f32_e64 v48, v48, v238
	v_add_f32_e64 v49, v49, v239
; #define MFMA(a, b, c) __builtin_amdgcn_mfma_f32_32x32x16_bf16((a), (b), (c), 0, 0, 0)
; DI void softmax_tile(f32x16 (&S)[2], float& lsum) {
;     f2_t ps = {0.f, 0.f};
; #pragma unroll
;     for (int t = 0; t < 2; ++t)
; #pragma unroll
;         for (int e = 0; e < 16; e += 2) {
;             f2_t pv; pv.x = __builtin_amdgcn_exp2f(S[t][e]); pv.y = __builtin_amdgcn_exp2f(S[t][e + 1]);
;             S[t][e] = pv.x; S[t][e + 1] = pv.y;
;             ps += pv;
;         }
;     lsum += ps.x + ps.y;
; }
; DI void pv_tile(const f32x16 (&S)[2], f32x16 (&O)[2], const bf16x8 (&vf)[8]) {
; #pragma unroll
;     for (int s = 0; s < 4; ++s) {
;         const bf16x8 pf = pack8(S[s >> 1], s & 1);
; #pragma unroll
;         for (int dt = 0; dt < 2; ++dt) O[dt] = MFMA(vf[2 * s + dt], pf, O[dt]);
;     }
; }
; template <int KIND>
; DI void attn_unit(const Params& p, int l, int b, int head, int qt, int qcol, int kcol, int vfeat, int gcol, int mixcol,
;                   int t1, int n1, int t2, int n2, char* smem) {
;     ...
;                 softmax_tile(S, l0);
;                 pv_tile(S, O0, vf);
.LBB0_134:
	s_nop 0
	v_exp_f32_e32 v64, v64
	v_exp_f32_e32 v65, v65
	v_exp_f32_e32 v66, v66
	v_exp_f32_e32 v67, v67
	v_exp_f32_e32 v68, v68
	v_exp_f32_e32 v69, v69
	v_exp_f32_e32 v70, v70
	v_exp_f32_e32 v71, v71
	v_add_f32_e64 v222, v64, 0
	v_add_f32_e64 v223, v65, 0
	v_cvt_pk_bf16_f32 v64, v64, v65
	v_add_f32_e64 v222, v66, v222
	v_add_f32_e64 v223, v67, v223
	v_cvt_pk_bf16_f32 v65, v66, v67
	v_cvt_pk_bf16_f32 v66, v68, v69
	v_cvt_pk_bf16_f32 v67, v70, v71
	v_add_f32_e64 v222, v68, v222
	v_add_f32_e64 v223, v69, v223
	v_exp_f32_e32 v72, v72
	s_waitcnt lgkmcnt(0)
	v_mfma_f32_32x32x16_bf16 v[16:31], v[156:159], v[64:67], v[16:31]
	v_exp_f32_e32 v73, v73
	v_add_f32_e64 v68, v70, v222
	v_add_f32_e64 v69, v71, v223
	v_exp_f32_e32 v70, v74
	v_exp_f32_e32 v71, v75
	v_exp_f32_e32 v74, v76
	v_exp_f32_e32 v75, v77
	v_exp_f32_e32 v76, v78
	v_mfma_f32_32x32x16_bf16 v[0:15], v[152:155], v[64:67], v[0:15]
	v_exp_f32_e32 v77, v79
	v_cvt_pk_bf16_f32 v64, v72, v73
	v_cvt_pk_bf16_f32 v65, v70, v71
	v_cvt_pk_bf16_f32 v66, v74, v75
	v_cvt_pk_bf16_f32 v67, v76, v77
	v_add_f32_e64 v68, v72, v68
	v_add_f32_e64 v69, v73, v69
	v_exp_f32_e32 v48, v48
	v_mfma_f32_32x32x16_bf16 v[16:31], v[148:151], v[64:67], v[16:31]
	v_exp_f32_e32 v49, v49
	v_add_f32_e64 v68, v70, v68
	v_add_f32_e64 v69, v71, v69
	v_exp_f32_e32 v70, v50
	v_exp_f32_e32 v71, v51
	v_exp_f32_e32 v52, v52
	v_exp_f32_e32 v53, v53
	v_exp_f32_e32 v54, v54
	v_mfma_f32_32x32x16_bf16 v[0:15], v[144:147], v[64:67], v[0:15]
	v_exp_f32_e32 v55, v55
	v_add_f32_e64 v68, v74, v68
	v_add_f32_e64 v69, v75, v69
	v_cvt_pk_bf16_f32 v50, v52, v53
	v_add_f32_e64 v68, v76, v68
	v_add_f32_e64 v69, v77, v69
	v_cvt_pk_bf16_f32 v51, v54, v55
	v_add_f32_e64 v68, v48, v68
	v_add_f32_e64 v69, v49, v69
	v_cvt_pk_bf16_f32 v48, v48, v49
	v_cvt_pk_bf16_f32 v49, v70, v71
	v_exp_f32_e32 v56, v56
	v_exp_f32_e32 v57, v57
	v_mfma_f32_32x32x16_bf16 v[16:31], v[140:143], v[48:51], v[16:31]
	v_exp_f32_e32 v58, v58
	v_exp_f32_e32 v59, v59
	v_exp_f32_e32 v60, v60
	v_exp_f32_e32 v61, v61
	v_exp_f32_e32 v62, v62
	v_exp_f32_e32 v63, v63
	v_add_f32_e64 v64, v70, v68
	v_add_f32_e64 v65, v71, v69
	v_mfma_f32_32x32x16_bf16 v[0:15], v[136:139], v[48:51], v[0:15]
	v_cvt_pk_bf16_f32 v48, v56, v57
	v_cvt_pk_bf16_f32 v49, v58, v59
	v_cvt_pk_bf16_f32 v50, v60, v61
	v_cvt_pk_bf16_f32 v51, v62, v63
	v_add_f32_e64 v52, v52, v64
	v_add_f32_e64 v53, v53, v65
	v_add_f32_e64 v52, v54, v52
	v_add_f32_e64 v53, v55, v53
	v_mfma_f32_32x32x16_bf16 v[16:31], v[132:135], v[48:51], v[16:31]
	v_add_f32_e64 v52, v56, v52
	v_add_f32_e64 v53, v57, v53
	v_add_f32_e64 v52, v58, v52
	v_add_f32_e64 v53, v59, v53
	v_add_f32_e64 v52, v60, v52
	v_add_f32_e64 v53, v61, v53
	v_add_f32_e64 v52, v62, v52
	v_add_f32_e64 v53, v63, v53
	v_mfma_f32_32x32x16_bf16 v[0:15], v[128:131], v[48:51], v[0:15]
	v_add_f32_e32 v52, v52, v53
	v_add_f32_e32 v179, v179, v52
